# ffn_up epilogue row blocks in packed f32 (v_pk_mul/fma/add_f32 on register pairs, exp/rcp scalar): same per-element operations
# speedup vs baseline: 1.0056x; 1.0056x over previous
.LBB0_1012:
	v_mov_b32_e32 v155, v128
	s_nop 1
	v_readlane_b32 s38, v252, 2
	v_readlane_b32 s39, v252, 3
	v_readlane_b32 s40, v252, 4
	v_readlane_b32 s41, v252, 5
	v_lshlrev_b32_sdwa v240, v151, v155 dst_sel:DWORD dst_unused:UNUSED_PAD src0_sel:DWORD src1_sel:BYTE_0
	v_and_b32_e32 v240, 56, v240
	v_lshl_or_b32 v240, s4, 7, v240
	v_ashrrev_i32_e32 v241, 31, v240
	v_lshlrev_b64 v[240:241], 2, v[240:241]
	v_lshl_add_u64 v[232:233], s[38:39], 0, v[240:241]
	v_lshl_add_u64 v[234:235], s[8:9], 0, v[240:241]
	v_lshl_add_u64 v[236:237], s[10:11], 0, v[240:241]
	v_lshl_add_u64 v[238:239], s[40:41], 0, v[240:241]
	global_load_dwordx4 v[200:203], v[232:233], off
	global_load_dwordx4 v[204:207], v[232:233], off offset:16
	global_load_dwordx4 v[208:211], v[234:235], off
	global_load_dwordx4 v[212:215], v[234:235], off offset:16
	global_load_dwordx4 v[216:219], v[236:237], off
	global_load_dwordx4 v[220:223], v[236:237], off offset:16
	global_load_dwordx4 v[224:227], v[238:239], off
	global_load_dwordx4 v[228:231], v[238:239], off offset:16
	s_mov_b32 s0, 0x12000
	v_and_b32_e32 v134, 15, v155
	v_ashrrev_i32_e32 v156, 8, v155
	v_mul_u32_u24_e32 v134, 0x210, v134
	v_lshlrev_b32_e32 v157, 1, v155
	v_mad_i32_i24 v134, v156, s0, v134
	v_and_b32_e32 v157, 0x180, v157
	v_and_b32_e32 v158, 48, v155
	v_add3_u32 v134, v134, v157, v158
	ds_write_b128 v134, v[124:127]
	ds_write_b128 v134, v[120:123] offset:64
	ds_write_b128 v134, v[116:119] offset:8448
	ds_write_b128 v134, v[112:115] offset:8512
	ds_write_b128 v134, v[108:111] offset:16896
	ds_write_b128 v134, v[104:107] offset:16960
	ds_write_b128 v134, v[100:103] offset:25344
	ds_write_b128 v134, v[96:99] offset:25408
	ds_write_b128 v134, v[92:95] offset:33792
	ds_write_b128 v134, v[88:91] offset:33856
	ds_write_b128 v134, v[84:87] offset:42240
	ds_write_b128 v134, v[80:83] offset:42304
	ds_write_b128 v134, v[76:79] offset:50688
	ds_write_b128 v134, v[72:75] offset:50752
	ds_write_b128 v134, v[68:71] offset:59136
	ds_write_b128 v134, v[64:67] offset:59200
	v_add_u32_e32 v107, s5, v156
	v_cmp_lt_i32_e32 vcc, s13, v107
	s_waitcnt lgkmcnt(0)
	s_barrier
	s_and_saveexec_b64 s[0:1], vcc
	s_xor_b64 s[0:1], exec, s[0:1]
	v_add_u32_e32 v64, 0xffffff78, v107
	v_mul_hi_u32 v65, v64, s12
	v_lshrrev_b32_e32 v65, 1, v65
	v_lshl_add_u32 v116, v65, 8, v149
	v_lshl_add_u32 v65, v65, 1, v65
	v_sub_u32_e32 v102, v64, v65
	s_or_saveexec_b64 s[0:1], s[0:1]
	v_mov_b32_e32 v117, 0x100
	s_xor_b64 exec, exec, s[0:1]
	v_mul_hi_i32 v64, v107, s14
	v_lshrrev_b32_e32 v65, 31, v64
	v_ashrrev_i32_e32 v64, 3, v64
	v_add_u32_e32 v64, v64, v65
	v_lshlrev_b32_e32 v116, 11, v64
	v_lshl_add_u32 v64, v64, 4, v64
	v_sub_u32_e32 v102, v107, v64
	v_mov_b32_e32 v117, 0x800
	s_or_b64 exec, exec, s[0:1]
	v_lshlrev_b32_sdwa v64, v151, v155 dst_sel:DWORD dst_unused:UNUSED_PAD src0_sel:DWORD src1_sel:BYTE_0
	v_and_b32_e32 v103, 56, v64
	v_lshl_or_b32 v96, s4, 7, v103
	v_ashrrev_i32_e32 v97, 31, v96
	v_readlane_b32 s36, v252, 0
	v_lshlrev_b64 v[76:77], 2, v[96:97]
	v_readlane_b32 s38, v252, 2
	v_readlane_b32 s39, v252, 3
	v_readlane_b32 s40, v252, 4
	v_readlane_b32 s41, v252, 5
	v_lshl_add_u64 v[98:99], s[38:39], 0, v[76:77]
	v_lshl_add_u64 v[68:69], s[8:9], 0, v[76:77]
	s_waitcnt vmcnt(0)
	v_mov_b64_e32 v[80:81], v[200:201]
	v_mov_b64_e32 v[82:83], v[202:203]
	v_mov_b64_e32 v[64:65], v[204:205]
	v_mov_b64_e32 v[66:67], v[206:207]
	v_mov_b64_e32 v[84:85], v[208:209]
	v_mov_b64_e32 v[86:87], v[210:211]
	v_mov_b64_e32 v[72:73], v[212:213]
	v_mov_b64_e32 v[74:75], v[214:215]
	v_lshl_add_u64 v[68:69], s[10:11], 0, v[76:77]
	v_lshl_add_u64 v[100:101], s[40:41], 0, v[76:77]
	v_mov_b64_e32 v[88:89], v[216:217]
	v_mov_b64_e32 v[90:91], v[218:219]
	s_nop 0
	v_mov_b64_e32 v[68:69], v[220:221]
	v_mov_b64_e32 v[70:71], v[222:223]
	s_nop 0
	v_mov_b64_e32 v[92:93], v[224:225]
	v_mov_b64_e32 v[94:95], v[226:227]
	v_mov_b64_e32 v[76:77], v[228:229]
	v_mov_b64_e32 v[78:79], v[230:231]
	global_load_dwordx4 v[200:203], v[232:233], off offset:256
	global_load_dwordx4 v[204:207], v[232:233], off offset:272
	global_load_dwordx4 v[208:211], v[234:235], off offset:256
	global_load_dwordx4 v[212:215], v[234:235], off offset:272
	global_load_dwordx4 v[216:219], v[236:237], off offset:256
	global_load_dwordx4 v[220:223], v[236:237], off offset:272
	global_load_dwordx4 v[224:227], v[238:239], off offset:256
	global_load_dwordx4 v[228:231], v[238:239], off offset:272
	v_bfe_u32 v110, v155, 3, 5
	v_lshlrev_b32_e32 v112, 2, v103
	v_mad_u64_u32 v[102:103], s[4:5], v102, s15, -1
	v_mul_i32_i24_e32 v106, 0x12000, v156
	v_mul_u32_u24_e32 v104, 0x210, v110
	v_add_u32_e32 v103, v102, v110
	v_cmp_gt_u32_sdwa s[0:1], v155, v153 src0_sel:BYTE_0 src1_sel:DWORD
	v_add3_u32 v104, v106, v104, v112
	v_cmp_lt_i32_e64 s[4:5], v103, v117
	v_add_u32_e32 v108, 0xfffffdf0, v104
	s_and_b64 s[6:7], s[0:1], s[4:5]
	v_readlane_b32 s37, v252, 1
	v_readlane_b32 s42, v252, 6
	v_readlane_b32 s43, v252, 7
	v_readlane_b32 s44, v252, 8
	v_readlane_b32 s45, v252, 9
	v_readlane_b32 s46, v252, 10
	v_readlane_b32 s47, v252, 11
	v_readlane_b32 s48, v252, 12
	v_readlane_b32 s49, v252, 13
	v_readlane_b32 s50, v252, 14
	v_readlane_b32 s51, v252, 15
	s_and_saveexec_b64 s[4:5], s[6:7]
	s_cbranch_execz .LBB0_1018
	s_mov_b32 s98, 0xbfb8aa3b
	ds_read_b128 v[118:121], v104
	ds_read_b128 v[164:167], v104 offset:16
	ds_read_b128 v[122:125], v108
	ds_read_b128 v[156:159], v108 offset:16
	ds_read_b128 v[160:163], v104 offset:528
	ds_read_b128 v[168:171], v104 offset:544
	ds_read_b128 v[172:175], v104 offset:256
	ds_read_b128 v[176:179], v104 offset:272
	s_waitcnt lgkmcnt(6)
	v_pk_mul_f32 v[118:119], v[84:85], v[118:119]
	v_pk_mul_f32 v[120:121], v[86:87], v[120:121]
	v_pk_mul_f32 v[164:165], v[72:73], v[164:165]
	v_pk_mul_f32 v[166:167], v[74:75], v[166:167]
	s_waitcnt lgkmcnt(4)
	v_pk_fma_f32 v[118:119], v[80:81], v[122:123], v[118:119]
	v_pk_fma_f32 v[120:121], v[82:83], v[124:125], v[120:121]
	v_pk_fma_f32 v[164:165], v[64:65], v[156:157], v[164:165]
	v_pk_fma_f32 v[166:167], v[66:67], v[158:159], v[166:167]
	s_waitcnt lgkmcnt(2)
	v_pk_fma_f32 v[118:119], v[88:89], v[160:161], v[118:119]
	v_pk_fma_f32 v[120:121], v[90:91], v[162:163], v[120:121]
	v_pk_fma_f32 v[164:165], v[68:69], v[168:169], v[164:165]
	v_pk_fma_f32 v[166:167], v[70:71], v[170:171], v[166:167]
	v_pk_add_f32 v[118:119], v[92:93], v[118:119]
	v_pk_add_f32 v[120:121], v[94:95], v[120:121]
	v_pk_add_f32 v[164:165], v[76:77], v[164:165]
	v_pk_add_f32 v[166:167], v[78:79], v[166:167]
	v_pk_mul_f32 v[122:123], v[118:119], s[98:99] op_sel_hi:[1,0]
	v_pk_mul_f32 v[124:125], v[120:121], s[98:99] op_sel_hi:[1,0]
	v_pk_mul_f32 v[156:157], v[164:165], s[98:99] op_sel_hi:[1,0]
	v_pk_mul_f32 v[158:159], v[166:167], s[98:99] op_sel_hi:[1,0]
	v_exp_f32_e32 v122, v122
	v_exp_f32_e32 v123, v123
	v_exp_f32_e32 v124, v124
	v_exp_f32_e32 v125, v125
	v_exp_f32_e32 v156, v156
	v_exp_f32_e32 v157, v157
	v_exp_f32_e32 v158, v158
	v_exp_f32_e32 v159, v159
	v_pk_add_f32 v[122:123], v[122:123], 1.0 op_sel_hi:[1,0]
	v_pk_add_f32 v[124:125], v[124:125], 1.0 op_sel_hi:[1,0]
	v_pk_add_f32 v[156:157], v[156:157], 1.0 op_sel_hi:[1,0]
	v_pk_add_f32 v[158:159], v[158:159], 1.0 op_sel_hi:[1,0]
	v_rcp_f32_e32 v122, v122
	v_rcp_f32_e32 v123, v123
	v_rcp_f32_e32 v124, v124
	v_rcp_f32_e32 v125, v125
	v_rcp_f32_e32 v156, v156
	v_rcp_f32_e32 v157, v157
	v_rcp_f32_e32 v158, v158
	v_rcp_f32_e32 v159, v159
	v_pk_mul_f32 v[118:119], v[118:119], v[122:123]
	v_pk_mul_f32 v[120:121], v[120:121], v[124:125]
	v_pk_mul_f32 v[164:165], v[164:165], v[156:157]
	v_pk_mul_f32 v[166:167], v[166:167], v[158:159]
	s_waitcnt lgkmcnt(0)
	v_pk_mul_f32 v[118:119], v[172:173], v[118:119]
	v_pk_mul_f32 v[120:121], v[174:175], v[120:121]
	v_pk_mul_f32 v[164:165], v[176:177], v[164:165]
	v_pk_mul_f32 v[166:167], v[178:179], v[166:167]
	v_cvt_pk_bf16_f32 v248, v118, v119
	v_cvt_pk_bf16_f32 v249, v120, v121
	v_cvt_pk_bf16_f32 v250, v164, v165
	v_cvt_pk_bf16_f32 v251, v166, v167
	v_add_u32_e32 v103, v103, v116
	v_mov_b64_e32 v[114:115], s[52:53]
	v_mad_i64_i32 v[114:115], s[6:7], v103, s16, v[114:115]
	v_lshl_add_u64 v[114:115], v[96:97], 1, v[114:115]
	global_store_dwordx4 v[114:115], v[248:251], off
.LBB0_1018:
	s_or_b64 exec, exec, s[4:5]
	v_or_b32_e32 v113, 32, v110
	v_mul_u32_u24_e32 v103, 0x210, v113
	v_add3_u32 v103, v106, v103, v112
	v_add_u32_e32 v105, v102, v113
	v_add_u32_e32 v109, 0xfffffdf0, v103
	v_cmp_lt_i32_e64 s[4:5], v105, v117
	s_and_saveexec_b64 s[6:7], s[4:5]
	s_cbranch_execz .LBB0_1020
	s_mov_b32 s98, 0xbfb8aa3b
	ds_read_b128 v[118:121], v103
	ds_read_b128 v[164:167], v103 offset:16
	ds_read_b128 v[122:125], v109
	ds_read_b128 v[156:159], v109 offset:16
	ds_read_b128 v[160:163], v103 offset:528
	ds_read_b128 v[168:171], v103 offset:544
	ds_read_b128 v[172:175], v103 offset:256
	ds_read_b128 v[176:179], v103 offset:272
	s_waitcnt lgkmcnt(6)
	v_pk_mul_f32 v[118:119], v[84:85], v[118:119]
	v_pk_mul_f32 v[120:121], v[86:87], v[120:121]
	v_pk_mul_f32 v[164:165], v[72:73], v[164:165]
	v_pk_mul_f32 v[166:167], v[74:75], v[166:167]
	s_waitcnt lgkmcnt(4)
	v_pk_fma_f32 v[118:119], v[80:81], v[122:123], v[118:119]
	v_pk_fma_f32 v[120:121], v[82:83], v[124:125], v[120:121]
	v_pk_fma_f32 v[164:165], v[64:65], v[156:157], v[164:165]
	v_pk_fma_f32 v[166:167], v[66:67], v[158:159], v[166:167]
	s_waitcnt lgkmcnt(2)
	v_pk_fma_f32 v[118:119], v[88:89], v[160:161], v[118:119]
	v_pk_fma_f32 v[120:121], v[90:91], v[162:163], v[120:121]
	v_pk_fma_f32 v[164:165], v[68:69], v[168:169], v[164:165]
	v_pk_fma_f32 v[166:167], v[70:71], v[170:171], v[166:167]
	v_pk_add_f32 v[118:119], v[92:93], v[118:119]
	v_pk_add_f32 v[120:121], v[94:95], v[120:121]
	v_pk_add_f32 v[164:165], v[76:77], v[164:165]
	v_pk_add_f32 v[166:167], v[78:79], v[166:167]
	v_pk_mul_f32 v[122:123], v[118:119], s[98:99] op_sel_hi:[1,0]
	v_pk_mul_f32 v[124:125], v[120:121], s[98:99] op_sel_hi:[1,0]
	v_pk_mul_f32 v[156:157], v[164:165], s[98:99] op_sel_hi:[1,0]
	v_pk_mul_f32 v[158:159], v[166:167], s[98:99] op_sel_hi:[1,0]
	v_exp_f32_e32 v122, v122
	v_exp_f32_e32 v123, v123
	v_exp_f32_e32 v124, v124
	v_exp_f32_e32 v125, v125
	v_exp_f32_e32 v156, v156
	v_exp_f32_e32 v157, v157
	v_exp_f32_e32 v158, v158
	v_exp_f32_e32 v159, v159
	v_pk_add_f32 v[122:123], v[122:123], 1.0 op_sel_hi:[1,0]
	v_pk_add_f32 v[124:125], v[124:125], 1.0 op_sel_hi:[1,0]
	v_pk_add_f32 v[156:157], v[156:157], 1.0 op_sel_hi:[1,0]
	v_pk_add_f32 v[158:159], v[158:159], 1.0 op_sel_hi:[1,0]
	v_rcp_f32_e32 v122, v122
	v_rcp_f32_e32 v123, v123
	v_rcp_f32_e32 v124, v124
	v_rcp_f32_e32 v125, v125
	v_rcp_f32_e32 v156, v156
	v_rcp_f32_e32 v157, v157
	v_rcp_f32_e32 v158, v158
	v_rcp_f32_e32 v159, v159
	v_pk_mul_f32 v[118:119], v[118:119], v[122:123]
	v_pk_mul_f32 v[120:121], v[120:121], v[124:125]
	v_pk_mul_f32 v[164:165], v[164:165], v[156:157]
	v_pk_mul_f32 v[166:167], v[166:167], v[158:159]
	s_waitcnt lgkmcnt(0)
	v_pk_mul_f32 v[118:119], v[172:173], v[118:119]
	v_pk_mul_f32 v[120:121], v[174:175], v[120:121]
	v_pk_mul_f32 v[164:165], v[176:177], v[164:165]
	v_pk_mul_f32 v[166:167], v[178:179], v[166:167]
	v_cvt_pk_bf16_f32 v248, v118, v119
	v_cvt_pk_bf16_f32 v249, v120, v121
	v_cvt_pk_bf16_f32 v250, v164, v165
	v_cvt_pk_bf16_f32 v251, v166, v167
	v_add_u32_e32 v105, v105, v116
	v_mov_b64_e32 v[114:115], s[52:53]
	v_mad_i64_i32 v[114:115], s[4:5], v105, s16, v[114:115]
	v_lshl_add_u64 v[114:115], v[96:97], 1, v[114:115]
	global_store_dwordx4 v[114:115], v[248:251], off
.LBB0_1020:
	s_or_b64 exec, exec, s[6:7]
	v_or_b32_e32 v114, 64, v110
	v_mul_u32_u24_e32 v105, 0x210, v114
	v_add3_u32 v105, v106, v105, v112
	v_add_u32_e32 v115, v102, v114
	v_add_u32_e32 v111, 0xfffffdf0, v105
	v_cmp_lt_i32_e64 s[4:5], v115, v117
	s_and_saveexec_b64 s[6:7], s[4:5]
	s_cbranch_execz .LBB0_1022
	s_mov_b32 s98, 0xbfb8aa3b
	ds_read_b128 v[118:121], v105
	ds_read_b128 v[164:167], v105 offset:16
	ds_read_b128 v[122:125], v111
	ds_read_b128 v[156:159], v111 offset:16
	ds_read_b128 v[160:163], v105 offset:528
	ds_read_b128 v[168:171], v105 offset:544
	ds_read_b128 v[172:175], v105 offset:256
	ds_read_b128 v[176:179], v105 offset:272
	s_waitcnt lgkmcnt(6)
	v_pk_mul_f32 v[118:119], v[84:85], v[118:119]
	v_pk_mul_f32 v[120:121], v[86:87], v[120:121]
	v_pk_mul_f32 v[164:165], v[72:73], v[164:165]
	v_pk_mul_f32 v[166:167], v[74:75], v[166:167]
	s_waitcnt lgkmcnt(4)
	v_pk_fma_f32 v[118:119], v[80:81], v[122:123], v[118:119]
	v_pk_fma_f32 v[120:121], v[82:83], v[124:125], v[120:121]
	v_pk_fma_f32 v[164:165], v[64:65], v[156:157], v[164:165]
	v_pk_fma_f32 v[166:167], v[66:67], v[158:159], v[166:167]
	s_waitcnt lgkmcnt(2)
	v_pk_fma_f32 v[118:119], v[88:89], v[160:161], v[118:119]
	v_pk_fma_f32 v[120:121], v[90:91], v[162:163], v[120:121]
	v_pk_fma_f32 v[164:165], v[68:69], v[168:169], v[164:165]
	v_pk_fma_f32 v[166:167], v[70:71], v[170:171], v[166:167]
	v_pk_add_f32 v[118:119], v[92:93], v[118:119]
	v_pk_add_f32 v[120:121], v[94:95], v[120:121]
	v_pk_add_f32 v[164:165], v[76:77], v[164:165]
	v_pk_add_f32 v[166:167], v[78:79], v[166:167]
	v_pk_mul_f32 v[122:123], v[118:119], s[98:99] op_sel_hi:[1,0]
	v_pk_mul_f32 v[124:125], v[120:121], s[98:99] op_sel_hi:[1,0]
	v_pk_mul_f32 v[156:157], v[164:165], s[98:99] op_sel_hi:[1,0]
	v_pk_mul_f32 v[158:159], v[166:167], s[98:99] op_sel_hi:[1,0]
	v_exp_f32_e32 v122, v122
	v_exp_f32_e32 v123, v123
	v_exp_f32_e32 v124, v124
	v_exp_f32_e32 v125, v125
	v_exp_f32_e32 v156, v156
	v_exp_f32_e32 v157, v157
	v_exp_f32_e32 v158, v158
	v_exp_f32_e32 v159, v159
	v_pk_add_f32 v[122:123], v[122:123], 1.0 op_sel_hi:[1,0]
	v_pk_add_f32 v[124:125], v[124:125], 1.0 op_sel_hi:[1,0]
	v_pk_add_f32 v[156:157], v[156:157], 1.0 op_sel_hi:[1,0]
	v_pk_add_f32 v[158:159], v[158:159], 1.0 op_sel_hi:[1,0]
	v_rcp_f32_e32 v122, v122
	v_rcp_f32_e32 v123, v123
	v_rcp_f32_e32 v124, v124
	v_rcp_f32_e32 v125, v125
	v_rcp_f32_e32 v156, v156
	v_rcp_f32_e32 v157, v157
	v_rcp_f32_e32 v158, v158
	v_rcp_f32_e32 v159, v159
	v_pk_mul_f32 v[118:119], v[118:119], v[122:123]
	v_pk_mul_f32 v[120:121], v[120:121], v[124:125]
	v_pk_mul_f32 v[164:165], v[164:165], v[156:157]
	v_pk_mul_f32 v[166:167], v[166:167], v[158:159]
	s_waitcnt lgkmcnt(0)
	v_pk_mul_f32 v[118:119], v[172:173], v[118:119]
	v_pk_mul_f32 v[120:121], v[174:175], v[120:121]
	v_pk_mul_f32 v[164:165], v[176:177], v[164:165]
	v_pk_mul_f32 v[166:167], v[178:179], v[166:167]
	v_cvt_pk_bf16_f32 v248, v118, v119
	v_cvt_pk_bf16_f32 v249, v120, v121
	v_cvt_pk_bf16_f32 v250, v164, v165
	v_cvt_pk_bf16_f32 v251, v166, v167
	v_add_u32_e32 v115, v115, v116
	v_mov_b64_e32 v[122:123], s[52:53]
	v_mad_i64_i32 v[122:123], s[4:5], v115, s16, v[122:123]
	v_lshl_add_u64 v[122:123], v[96:97], 1, v[122:123]
	global_store_dwordx4 v[122:123], v[248:251], off
.LBB0_1022:
	s_or_b64 exec, exec, s[6:7]
	v_or_b32_e32 v115, 0x60, v110
	v_mul_u32_u24_e32 v118, 0x210, v115
	v_add_u32_e32 v102, v102, v115
	v_cmp_ne_u32_e64 s[4:5], 31, v110
	v_add3_u32 v106, v106, v118, v112
	v_cmp_lt_i32_e64 s[6:7], v102, v117
	v_add_u32_e32 v112, 0xfffffdf0, v106
	s_and_b64 s[24:25], s[4:5], s[6:7]
	s_and_saveexec_b64 s[6:7], s[24:25]
	s_cbranch_execz .LBB0_1024
	s_mov_b32 s98, 0xbfb8aa3b
	ds_read_b128 v[118:121], v106
	ds_read_b128 v[164:167], v106 offset:16
	ds_read_b128 v[122:125], v112
	ds_read_b128 v[156:159], v112 offset:16
	ds_read_b128 v[160:163], v106 offset:528
	ds_read_b128 v[168:171], v106 offset:544
	ds_read_b128 v[172:175], v106 offset:256
	ds_read_b128 v[176:179], v106 offset:272
	s_waitcnt lgkmcnt(6)
	v_pk_mul_f32 v[118:119], v[84:85], v[118:119]
	v_pk_mul_f32 v[120:121], v[86:87], v[120:121]
	v_pk_mul_f32 v[164:165], v[72:73], v[164:165]
	v_pk_mul_f32 v[166:167], v[74:75], v[166:167]
	s_waitcnt lgkmcnt(4)
	v_pk_fma_f32 v[118:119], v[80:81], v[122:123], v[118:119]
	v_pk_fma_f32 v[120:121], v[82:83], v[124:125], v[120:121]
	v_pk_fma_f32 v[164:165], v[64:65], v[156:157], v[164:165]
	v_pk_fma_f32 v[166:167], v[66:67], v[158:159], v[166:167]
	s_waitcnt lgkmcnt(2)
	v_pk_fma_f32 v[118:119], v[88:89], v[160:161], v[118:119]
	v_pk_fma_f32 v[120:121], v[90:91], v[162:163], v[120:121]
	v_pk_fma_f32 v[164:165], v[68:69], v[168:169], v[164:165]
	v_pk_fma_f32 v[166:167], v[70:71], v[170:171], v[166:167]
	v_pk_add_f32 v[118:119], v[92:93], v[118:119]
	v_pk_add_f32 v[120:121], v[94:95], v[120:121]
	v_pk_add_f32 v[164:165], v[76:77], v[164:165]
	v_pk_add_f32 v[166:167], v[78:79], v[166:167]
	v_pk_mul_f32 v[122:123], v[118:119], s[98:99] op_sel_hi:[1,0]
	v_pk_mul_f32 v[124:125], v[120:121], s[98:99] op_sel_hi:[1,0]
	v_pk_mul_f32 v[156:157], v[164:165], s[98:99] op_sel_hi:[1,0]
	v_pk_mul_f32 v[158:159], v[166:167], s[98:99] op_sel_hi:[1,0]
	v_exp_f32_e32 v122, v122
	v_exp_f32_e32 v123, v123
	v_exp_f32_e32 v124, v124
	v_exp_f32_e32 v125, v125
	v_exp_f32_e32 v156, v156
	v_exp_f32_e32 v157, v157
	v_exp_f32_e32 v158, v158
	v_exp_f32_e32 v159, v159
	v_pk_add_f32 v[122:123], v[122:123], 1.0 op_sel_hi:[1,0]
	v_pk_add_f32 v[124:125], v[124:125], 1.0 op_sel_hi:[1,0]
	v_pk_add_f32 v[156:157], v[156:157], 1.0 op_sel_hi:[1,0]
	v_pk_add_f32 v[158:159], v[158:159], 1.0 op_sel_hi:[1,0]
	v_rcp_f32_e32 v122, v122
	v_rcp_f32_e32 v123, v123
	v_rcp_f32_e32 v124, v124
	v_rcp_f32_e32 v125, v125
	v_rcp_f32_e32 v156, v156
	v_rcp_f32_e32 v157, v157
	v_rcp_f32_e32 v158, v158
	v_rcp_f32_e32 v159, v159
	v_pk_mul_f32 v[118:119], v[118:119], v[122:123]
	v_pk_mul_f32 v[120:121], v[120:121], v[124:125]
	v_pk_mul_f32 v[164:165], v[164:165], v[156:157]
	v_pk_mul_f32 v[166:167], v[166:167], v[158:159]
	s_waitcnt lgkmcnt(0)
	v_pk_mul_f32 v[118:119], v[172:173], v[118:119]
	v_pk_mul_f32 v[120:121], v[174:175], v[120:121]
	v_pk_mul_f32 v[164:165], v[176:177], v[164:165]
	v_pk_mul_f32 v[166:167], v[178:179], v[166:167]
	v_cvt_pk_bf16_f32 v248, v118, v119
	v_cvt_pk_bf16_f32 v249, v120, v121
	v_cvt_pk_bf16_f32 v250, v164, v165
	v_cvt_pk_bf16_f32 v251, v166, v167
	v_add_u32_e32 v70, v102, v116
	v_mov_b64_e32 v[68:69], s[52:53]
	v_mad_i64_i32 v[68:69], s[24:25], v70, s16, v[68:69]
	v_lshl_add_u64 v[68:69], v[96:97], 1, v[68:69]
	global_store_dwordx4 v[68:69], v[248:251], off
.LBB0_1024:
	s_or_b64 exec, exec, s[6:7]
	s_barrier
	ds_write_b128 v134, v[60:63]
	ds_write_b128 v134, v[56:59] offset:64
	ds_write_b128 v134, v[48:51] offset:8448
	ds_write_b128 v134, v[44:47] offset:8512
	ds_write_b128 v134, v[40:43] offset:16896
	ds_write_b128 v134, v[36:39] offset:16960
	ds_write_b128 v134, v[32:35] offset:25344
	ds_write_b128 v134, v[28:31] offset:25408
	ds_write_b128 v134, v[24:27] offset:33792
	ds_write_b128 v134, v[20:23] offset:33856
	ds_write_b128 v134, v[16:19] offset:42240
	ds_write_b128 v134, v[12:15] offset:42304
	ds_write_b128 v134, v[8:11] offset:50688
	ds_write_b128 v134, v[4:7] offset:50752
	ds_write_b128 v134, v[0:3] offset:59136
	ds_write_b128 v134, v[52:55] offset:59200
	s_waitcnt lgkmcnt(0)
	s_barrier
	s_and_saveexec_b64 s[6:7], vcc
	s_xor_b64 s[6:7], exec, s[6:7]
	v_add_u32_e32 v0, 0xffffff78, v107
	v_mul_hi_u32 v1, v0, s12
	v_lshrrev_b32_e32 v1, 1, v1
	v_lshl_add_u32 v34, v1, 8, v149
	v_lshl_add_u32 v1, v1, 1, v1
	v_sub_u32_e32 v32, v0, v1
	s_or_saveexec_b64 s[6:7], s[6:7]
	v_mov_b32_e32 v35, 0x100
	s_xor_b64 exec, exec, s[6:7]
	v_mul_hi_i32 v0, v107, s14
	v_lshrrev_b32_e32 v1, 31, v0
	v_ashrrev_i32_e32 v0, 3, v0
	v_add_u32_e32 v0, v0, v1
	v_lshlrev_b32_e32 v34, 11, v0
	v_lshl_add_u32 v0, v0, 4, v0
	v_sub_u32_e32 v32, v107, v0
	v_mov_b32_e32 v35, 0x800
	s_or_b64 exec, exec, s[6:7]
	v_or_b32_e32 v4, 64, v96
	v_ashrrev_i32_e32 v5, 31, v4
	v_lshlrev_b64 v[4:5], 2, v[4:5]
	v_lshl_add_u64 v[6:7], s[8:9], 0, v[4:5]
	v_lshl_add_u64 v[4:5], s[10:11], 0, v[4:5]
	s_waitcnt vmcnt(0)
	v_mov_b64_e32 v[16:17], v[200:201]
	v_mov_b64_e32 v[18:19], v[202:203]
	v_mov_b64_e32 v[0:1], v[204:205]
	v_mov_b64_e32 v[2:3], v[206:207]
	v_mov_b64_e32 v[20:21], v[208:209]
	v_mov_b64_e32 v[22:23], v[210:211]
	v_mov_b64_e32 v[8:9], v[212:213]
	v_mov_b64_e32 v[10:11], v[214:215]
	v_mov_b64_e32 v[24:25], v[216:217]
	v_mov_b64_e32 v[26:27], v[218:219]
	s_nop 0
	v_mov_b64_e32 v[4:5], v[220:221]
	v_mov_b64_e32 v[6:7], v[222:223]
	s_nop 0
	v_mov_b64_e32 v[28:29], v[224:225]
	v_mov_b64_e32 v[30:31], v[226:227]
	v_mov_b64_e32 v[12:13], v[228:229]
	v_mov_b64_e32 v[14:15], v[230:231]
	v_mad_u64_u32 v[32:33], s[6:7], v32, s15, -1
	v_add_u32_e32 v33, v32, v110
	v_cmp_lt_i32_e32 vcc, v33, v35
	s_and_b64 s[6:7], s[0:1], vcc
	s_and_saveexec_b64 s[0:1], s[6:7]
	s_cbranch_execz .LBB0_1030
	s_mov_b32 s98, 0xbfb8aa3b
	ds_read_b128 v[36:39], v104
	ds_read_b128 v[52:55], v104 offset:16
	ds_read_b128 v[40:43], v108
	ds_read_b128 v[44:47], v108 offset:16
	ds_read_b128 v[48:51], v104 offset:528
	ds_read_b128 v[56:59], v104 offset:544
	ds_read_b128 v[60:63], v104 offset:256
	ds_read_b128 v[64:67], v104 offset:272
	s_waitcnt lgkmcnt(6)
	v_pk_mul_f32 v[36:37], v[20:21], v[36:37]
	v_pk_mul_f32 v[38:39], v[22:23], v[38:39]
	v_pk_mul_f32 v[52:53], v[8:9], v[52:53]
	v_pk_mul_f32 v[54:55], v[10:11], v[54:55]
	s_waitcnt lgkmcnt(4)
	v_pk_fma_f32 v[36:37], v[16:17], v[40:41], v[36:37]
	v_pk_fma_f32 v[38:39], v[18:19], v[42:43], v[38:39]
	v_pk_fma_f32 v[52:53], v[0:1], v[44:45], v[52:53]
	v_pk_fma_f32 v[54:55], v[2:3], v[46:47], v[54:55]
	s_waitcnt lgkmcnt(2)
	v_pk_fma_f32 v[36:37], v[24:25], v[48:49], v[36:37]
	v_pk_fma_f32 v[38:39], v[26:27], v[50:51], v[38:39]
	v_pk_fma_f32 v[52:53], v[4:5], v[56:57], v[52:53]
	v_pk_fma_f32 v[54:55], v[6:7], v[58:59], v[54:55]
	v_pk_add_f32 v[36:37], v[28:29], v[36:37]
	v_pk_add_f32 v[38:39], v[30:31], v[38:39]
	v_pk_add_f32 v[52:53], v[12:13], v[52:53]
	v_pk_add_f32 v[54:55], v[14:15], v[54:55]
	v_pk_mul_f32 v[40:41], v[36:37], s[98:99] op_sel_hi:[1,0]
	v_pk_mul_f32 v[42:43], v[38:39], s[98:99] op_sel_hi:[1,0]
	v_pk_mul_f32 v[44:45], v[52:53], s[98:99] op_sel_hi:[1,0]
	v_pk_mul_f32 v[46:47], v[54:55], s[98:99] op_sel_hi:[1,0]
	v_exp_f32_e32 v40, v40
	v_exp_f32_e32 v41, v41
	v_exp_f32_e32 v42, v42
	v_exp_f32_e32 v43, v43
	v_exp_f32_e32 v44, v44
	v_exp_f32_e32 v45, v45
	v_exp_f32_e32 v46, v46
	v_exp_f32_e32 v47, v47
	v_pk_add_f32 v[40:41], v[40:41], 1.0 op_sel_hi:[1,0]
	v_pk_add_f32 v[42:43], v[42:43], 1.0 op_sel_hi:[1,0]
	v_pk_add_f32 v[44:45], v[44:45], 1.0 op_sel_hi:[1,0]
	v_pk_add_f32 v[46:47], v[46:47], 1.0 op_sel_hi:[1,0]
	v_rcp_f32_e32 v40, v40
	v_rcp_f32_e32 v41, v41
	v_rcp_f32_e32 v42, v42
	v_rcp_f32_e32 v43, v43
	v_rcp_f32_e32 v44, v44
	v_rcp_f32_e32 v45, v45
	v_rcp_f32_e32 v46, v46
	v_rcp_f32_e32 v47, v47
	v_pk_mul_f32 v[36:37], v[36:37], v[40:41]
	v_pk_mul_f32 v[38:39], v[38:39], v[42:43]
	v_pk_mul_f32 v[52:53], v[52:53], v[44:45]
	v_pk_mul_f32 v[54:55], v[54:55], v[46:47]
	s_waitcnt lgkmcnt(0)
	v_pk_mul_f32 v[36:37], v[60:61], v[36:37]
	v_pk_mul_f32 v[38:39], v[62:63], v[38:39]
	v_pk_mul_f32 v[52:53], v[64:65], v[52:53]
	v_pk_mul_f32 v[54:55], v[66:67], v[54:55]
	v_cvt_pk_bf16_f32 v248, v36, v37
	v_cvt_pk_bf16_f32 v249, v38, v39
	v_cvt_pk_bf16_f32 v250, v52, v53
	v_cvt_pk_bf16_f32 v251, v54, v55
	v_add_u32_e32 v33, v33, v34
	v_mov_b64_e32 v[40:41], s[52:53]
	v_mad_i64_i32 v[40:41], s[6:7], v33, s16, v[40:41]
	v_lshl_add_u64 v[40:41], v[96:97], 1, v[40:41]
	global_store_dwordx4 v[40:41], v[248:251], off offset:128
.LBB0_1030:
	s_or_b64 exec, exec, s[0:1]
	v_add_u32_e32 v33, v32, v113
	v_cmp_lt_i32_e32 vcc, v33, v35
	s_and_saveexec_b64 s[0:1], vcc
	s_cbranch_execz .LBB0_1032
	s_mov_b32 s98, 0xbfb8aa3b
	ds_read_b128 v[36:39], v103
	ds_read_b128 v[52:55], v103 offset:16
	ds_read_b128 v[40:43], v109
	ds_read_b128 v[44:47], v109 offset:16
	ds_read_b128 v[48:51], v103 offset:528
	ds_read_b128 v[56:59], v103 offset:544
	ds_read_b128 v[60:63], v103 offset:256
	ds_read_b128 v[64:67], v103 offset:272
	s_waitcnt lgkmcnt(6)
	v_pk_mul_f32 v[36:37], v[20:21], v[36:37]
	v_pk_mul_f32 v[38:39], v[22:23], v[38:39]
	v_pk_mul_f32 v[52:53], v[8:9], v[52:53]
	v_pk_mul_f32 v[54:55], v[10:11], v[54:55]
	s_waitcnt lgkmcnt(4)
	v_pk_fma_f32 v[36:37], v[16:17], v[40:41], v[36:37]
	v_pk_fma_f32 v[38:39], v[18:19], v[42:43], v[38:39]
	v_pk_fma_f32 v[52:53], v[0:1], v[44:45], v[52:53]
	v_pk_fma_f32 v[54:55], v[2:3], v[46:47], v[54:55]
	s_waitcnt lgkmcnt(2)
	v_pk_fma_f32 v[36:37], v[24:25], v[48:49], v[36:37]
	v_pk_fma_f32 v[38:39], v[26:27], v[50:51], v[38:39]
	v_pk_fma_f32 v[52:53], v[4:5], v[56:57], v[52:53]
	v_pk_fma_f32 v[54:55], v[6:7], v[58:59], v[54:55]
	v_pk_add_f32 v[36:37], v[28:29], v[36:37]
	v_pk_add_f32 v[38:39], v[30:31], v[38:39]
	v_pk_add_f32 v[52:53], v[12:13], v[52:53]
	v_pk_add_f32 v[54:55], v[14:15], v[54:55]
	v_pk_mul_f32 v[40:41], v[36:37], s[98:99] op_sel_hi:[1,0]
	v_pk_mul_f32 v[42:43], v[38:39], s[98:99] op_sel_hi:[1,0]
	v_pk_mul_f32 v[44:45], v[52:53], s[98:99] op_sel_hi:[1,0]
	v_pk_mul_f32 v[46:47], v[54:55], s[98:99] op_sel_hi:[1,0]
	v_exp_f32_e32 v40, v40
	v_exp_f32_e32 v41, v41
	v_exp_f32_e32 v42, v42
	v_exp_f32_e32 v43, v43
	v_exp_f32_e32 v44, v44
	v_exp_f32_e32 v45, v45
	v_exp_f32_e32 v46, v46
	v_exp_f32_e32 v47, v47
	v_pk_add_f32 v[40:41], v[40:41], 1.0 op_sel_hi:[1,0]
	v_pk_add_f32 v[42:43], v[42:43], 1.0 op_sel_hi:[1,0]
	v_pk_add_f32 v[44:45], v[44:45], 1.0 op_sel_hi:[1,0]
	v_pk_add_f32 v[46:47], v[46:47], 1.0 op_sel_hi:[1,0]
	v_rcp_f32_e32 v40, v40
	v_rcp_f32_e32 v41, v41
	v_rcp_f32_e32 v42, v42
	v_rcp_f32_e32 v43, v43
	v_rcp_f32_e32 v44, v44
	v_rcp_f32_e32 v45, v45
	v_rcp_f32_e32 v46, v46
	v_rcp_f32_e32 v47, v47
	v_pk_mul_f32 v[36:37], v[36:37], v[40:41]
	v_pk_mul_f32 v[38:39], v[38:39], v[42:43]
	v_pk_mul_f32 v[52:53], v[52:53], v[44:45]
	v_pk_mul_f32 v[54:55], v[54:55], v[46:47]
	s_waitcnt lgkmcnt(0)
	v_pk_mul_f32 v[36:37], v[60:61], v[36:37]
	v_pk_mul_f32 v[38:39], v[62:63], v[38:39]
	v_pk_mul_f32 v[52:53], v[64:65], v[52:53]
	v_pk_mul_f32 v[54:55], v[66:67], v[54:55]
	v_cvt_pk_bf16_f32 v248, v36, v37
	v_cvt_pk_bf16_f32 v249, v38, v39
	v_cvt_pk_bf16_f32 v250, v52, v53
	v_cvt_pk_bf16_f32 v251, v54, v55
	v_add_u32_e32 v33, v33, v34
	v_mov_b64_e32 v[40:41], s[52:53]
	v_mad_i64_i32 v[40:41], s[6:7], v33, s16, v[40:41]
	v_lshl_add_u64 v[40:41], v[96:97], 1, v[40:41]
	global_store_dwordx4 v[40:41], v[248:251], off offset:128
.LBB0_1032:
	s_or_b64 exec, exec, s[0:1]
	v_add_u32_e32 v33, v32, v114
	v_cmp_lt_i32_e32 vcc, v33, v35
	s_and_saveexec_b64 s[0:1], vcc
	s_cbranch_execz .LBB0_1034
	s_mov_b32 s98, 0xbfb8aa3b
	ds_read_b128 v[36:39], v105
	ds_read_b128 v[52:55], v105 offset:16
	ds_read_b128 v[40:43], v111
	ds_read_b128 v[44:47], v111 offset:16
	ds_read_b128 v[48:51], v105 offset:528
	ds_read_b128 v[56:59], v105 offset:544
	ds_read_b128 v[60:63], v105 offset:256
	ds_read_b128 v[64:67], v105 offset:272
	s_waitcnt lgkmcnt(6)
	v_pk_mul_f32 v[36:37], v[20:21], v[36:37]
	v_pk_mul_f32 v[38:39], v[22:23], v[38:39]
	v_pk_mul_f32 v[52:53], v[8:9], v[52:53]
	v_pk_mul_f32 v[54:55], v[10:11], v[54:55]
	s_waitcnt lgkmcnt(4)
	v_pk_fma_f32 v[36:37], v[16:17], v[40:41], v[36:37]
	v_pk_fma_f32 v[38:39], v[18:19], v[42:43], v[38:39]
	v_pk_fma_f32 v[52:53], v[0:1], v[44:45], v[52:53]
	v_pk_fma_f32 v[54:55], v[2:3], v[46:47], v[54:55]
	s_waitcnt lgkmcnt(2)
	v_pk_fma_f32 v[36:37], v[24:25], v[48:49], v[36:37]
	v_pk_fma_f32 v[38:39], v[26:27], v[50:51], v[38:39]
	v_pk_fma_f32 v[52:53], v[4:5], v[56:57], v[52:53]
	v_pk_fma_f32 v[54:55], v[6:7], v[58:59], v[54:55]
	v_pk_add_f32 v[36:37], v[28:29], v[36:37]
	v_pk_add_f32 v[38:39], v[30:31], v[38:39]
	v_pk_add_f32 v[52:53], v[12:13], v[52:53]
	v_pk_add_f32 v[54:55], v[14:15], v[54:55]
	v_pk_mul_f32 v[40:41], v[36:37], s[98:99] op_sel_hi:[1,0]
	v_pk_mul_f32 v[42:43], v[38:39], s[98:99] op_sel_hi:[1,0]
	v_pk_mul_f32 v[44:45], v[52:53], s[98:99] op_sel_hi:[1,0]
	v_pk_mul_f32 v[46:47], v[54:55], s[98:99] op_sel_hi:[1,0]
	v_exp_f32_e32 v40, v40
	v_exp_f32_e32 v41, v41
	v_exp_f32_e32 v42, v42
	v_exp_f32_e32 v43, v43
	v_exp_f32_e32 v44, v44
	v_exp_f32_e32 v45, v45
	v_exp_f32_e32 v46, v46
	v_exp_f32_e32 v47, v47
	v_pk_add_f32 v[40:41], v[40:41], 1.0 op_sel_hi:[1,0]
	v_pk_add_f32 v[42:43], v[42:43], 1.0 op_sel_hi:[1,0]
	v_pk_add_f32 v[44:45], v[44:45], 1.0 op_sel_hi:[1,0]
	v_pk_add_f32 v[46:47], v[46:47], 1.0 op_sel_hi:[1,0]
	v_rcp_f32_e32 v40, v40
	v_rcp_f32_e32 v41, v41
	v_rcp_f32_e32 v42, v42
	v_rcp_f32_e32 v43, v43
	v_rcp_f32_e32 v44, v44
	v_rcp_f32_e32 v45, v45
	v_rcp_f32_e32 v46, v46
	v_rcp_f32_e32 v47, v47
	v_pk_mul_f32 v[36:37], v[36:37], v[40:41]
	v_pk_mul_f32 v[38:39], v[38:39], v[42:43]
	v_pk_mul_f32 v[52:53], v[52:53], v[44:45]
	v_pk_mul_f32 v[54:55], v[54:55], v[46:47]
	s_waitcnt lgkmcnt(0)
	v_pk_mul_f32 v[36:37], v[60:61], v[36:37]
	v_pk_mul_f32 v[38:39], v[62:63], v[38:39]
	v_pk_mul_f32 v[52:53], v[64:65], v[52:53]
	v_pk_mul_f32 v[54:55], v[66:67], v[54:55]
	v_cvt_pk_bf16_f32 v248, v36, v37
	v_cvt_pk_bf16_f32 v249, v38, v39
	v_cvt_pk_bf16_f32 v250, v52, v53
	v_cvt_pk_bf16_f32 v251, v54, v55
	v_add_u32_e32 v33, v33, v34
	v_mov_b64_e32 v[40:41], s[52:53]
	v_mad_i64_i32 v[40:41], s[6:7], v33, s16, v[40:41]
	v_lshl_add_u64 v[40:41], v[96:97], 1, v[40:41]
	global_store_dwordx4 v[40:41], v[248:251], off offset:128
.LBB0_1034:
	s_or_b64 exec, exec, s[0:1]
	v_add_u32_e32 v32, v32, v115
	v_cmp_lt_i32_e32 vcc, v32, v35
	s_and_b64 s[4:5], s[4:5], vcc
	s_and_saveexec_b64 s[0:1], s[4:5]
	s_cbranch_execz .LBB0_991
	s_mov_b32 s98, 0xbfb8aa3b
	ds_read_b128 v[36:39], v106
	ds_read_b128 v[52:55], v106 offset:16
	ds_read_b128 v[40:43], v112
	ds_read_b128 v[44:47], v112 offset:16
	ds_read_b128 v[48:51], v106 offset:528
	ds_read_b128 v[56:59], v106 offset:544
	ds_read_b128 v[60:63], v106 offset:256
	ds_read_b128 v[64:67], v106 offset:272
	s_waitcnt lgkmcnt(6)
	v_pk_mul_f32 v[36:37], v[20:21], v[36:37]
	v_pk_mul_f32 v[38:39], v[22:23], v[38:39]
	v_pk_mul_f32 v[52:53], v[8:9], v[52:53]
	v_pk_mul_f32 v[54:55], v[10:11], v[54:55]
	s_waitcnt lgkmcnt(4)
	v_pk_fma_f32 v[36:37], v[16:17], v[40:41], v[36:37]
	v_pk_fma_f32 v[38:39], v[18:19], v[42:43], v[38:39]
	v_pk_fma_f32 v[52:53], v[0:1], v[44:45], v[52:53]
	v_pk_fma_f32 v[54:55], v[2:3], v[46:47], v[54:55]
	s_waitcnt lgkmcnt(2)
	v_pk_fma_f32 v[36:37], v[24:25], v[48:49], v[36:37]
	v_pk_fma_f32 v[38:39], v[26:27], v[50:51], v[38:39]
	v_pk_fma_f32 v[52:53], v[4:5], v[56:57], v[52:53]
	v_pk_fma_f32 v[54:55], v[6:7], v[58:59], v[54:55]
	v_pk_add_f32 v[36:37], v[28:29], v[36:37]
	v_pk_add_f32 v[38:39], v[30:31], v[38:39]
	v_pk_add_f32 v[52:53], v[12:13], v[52:53]
	v_pk_add_f32 v[54:55], v[14:15], v[54:55]
	v_pk_mul_f32 v[40:41], v[36:37], s[98:99] op_sel_hi:[1,0]
	v_pk_mul_f32 v[42:43], v[38:39], s[98:99] op_sel_hi:[1,0]
	v_pk_mul_f32 v[44:45], v[52:53], s[98:99] op_sel_hi:[1,0]
	v_pk_mul_f32 v[46:47], v[54:55], s[98:99] op_sel_hi:[1,0]
	v_exp_f32_e32 v40, v40
	v_exp_f32_e32 v41, v41
	v_exp_f32_e32 v42, v42
	v_exp_f32_e32 v43, v43
	v_exp_f32_e32 v44, v44
	v_exp_f32_e32 v45, v45
	v_exp_f32_e32 v46, v46
	v_exp_f32_e32 v47, v47
	v_pk_add_f32 v[40:41], v[40:41], 1.0 op_sel_hi:[1,0]
	v_pk_add_f32 v[42:43], v[42:43], 1.0 op_sel_hi:[1,0]
	v_pk_add_f32 v[44:45], v[44:45], 1.0 op_sel_hi:[1,0]
	v_pk_add_f32 v[46:47], v[46:47], 1.0 op_sel_hi:[1,0]
	v_rcp_f32_e32 v40, v40
	v_rcp_f32_e32 v41, v41
	v_rcp_f32_e32 v42, v42
	v_rcp_f32_e32 v43, v43
	v_rcp_f32_e32 v44, v44
	v_rcp_f32_e32 v45, v45
	v_rcp_f32_e32 v46, v46
	v_rcp_f32_e32 v47, v47
	v_pk_mul_f32 v[36:37], v[36:37], v[40:41]
	v_pk_mul_f32 v[38:39], v[38:39], v[42:43]
	v_pk_mul_f32 v[52:53], v[52:53], v[44:45]
	v_pk_mul_f32 v[54:55], v[54:55], v[46:47]
	s_waitcnt lgkmcnt(0)
	v_pk_mul_f32 v[36:37], v[60:61], v[36:37]
	v_pk_mul_f32 v[38:39], v[62:63], v[38:39]
	v_pk_mul_f32 v[52:53], v[64:65], v[52:53]
	v_pk_mul_f32 v[54:55], v[66:67], v[54:55]
	v_cvt_pk_bf16_f32 v248, v36, v37
	v_cvt_pk_bf16_f32 v249, v38, v39
	v_cvt_pk_bf16_f32 v250, v52, v53
	v_cvt_pk_bf16_f32 v251, v54, v55
	v_add_u32_e32 v6, v32, v34
	v_mov_b64_e32 v[4:5], s[52:53]
	v_mad_i64_i32 v[4:5], s[4:5], v6, s16, v[4:5]
	v_lshl_add_u64 v[4:5], v[96:97], 1, v[4:5]
	global_store_dwordx4 v[4:5], v[248:251], off offset:128
	s_branch .LBB0_991

.LBB0_2003:
	v_mov_b32_e32 v160, v128
	s_nop 1
	v_lshlrev_b32_sdwa v240, v176, v160 dst_sel:DWORD dst_unused:UNUSED_PAD src0_sel:DWORD src1_sel:BYTE_0
	v_and_b32_e32 v240, 56, v240
	v_lshl_or_b32 v240, s20, 7, v240
	v_ashrrev_i32_e32 v241, 31, v240
	v_lshlrev_b64 v[240:241], 2, v[240:241]
	v_lshl_add_u64 v[232:233], s[8:9], 0, v[240:241]
	v_lshl_add_u64 v[234:235], s[12:13], 0, v[240:241]
	v_lshl_add_u64 v[236:237], s[14:15], 0, v[240:241]
	v_lshl_add_u64 v[238:239], s[10:11], 0, v[240:241]
	global_load_dwordx4 v[200:203], v[232:233], off
	global_load_dwordx4 v[204:207], v[232:233], off offset:16
	global_load_dwordx4 v[208:211], v[234:235], off
	global_load_dwordx4 v[212:215], v[234:235], off offset:16
	global_load_dwordx4 v[216:219], v[236:237], off
	global_load_dwordx4 v[220:223], v[236:237], off offset:16
	global_load_dwordx4 v[224:227], v[238:239], off
	global_load_dwordx4 v[228:231], v[238:239], off offset:16
	s_nop 0
	v_and_b32_e32 v132, 15, v160
	v_ashrrev_i32_e32 v161, 8, v160
	v_mul_u32_u24_e32 v132, 0x210, v132
	v_lshlrev_b32_e32 v162, 1, v160
	v_mad_i32_i24 v132, v161, s29, v132
	v_and_b32_e32 v162, 0x180, v162
	v_and_b32_e32 v163, 48, v160
	v_add3_u32 v132, v132, v162, v163
	ds_write_b128 v132, v[124:127]
	ds_write_b128 v132, v[120:123] offset:64
	ds_write_b128 v132, v[116:119] offset:8448
	ds_write_b128 v132, v[112:115] offset:8512
	ds_write_b128 v132, v[108:111] offset:16896
	ds_write_b128 v132, v[104:107] offset:16960
	ds_write_b128 v132, v[100:103] offset:25344
	ds_write_b128 v132, v[96:99] offset:25408
	ds_write_b128 v132, v[92:95] offset:33792
	ds_write_b128 v132, v[88:91] offset:33856
	ds_write_b128 v132, v[84:87] offset:42240
	ds_write_b128 v132, v[80:83] offset:42304
	ds_write_b128 v132, v[76:79] offset:50688
	ds_write_b128 v132, v[72:75] offset:50752
	ds_write_b128 v132, v[68:71] offset:59136
	ds_write_b128 v132, v[64:67] offset:59200
	v_add_u32_e32 v103, s21, v161
	v_cmp_lt_i32_e32 vcc, s17, v103
	s_waitcnt lgkmcnt(0)
	s_barrier
	s_and_saveexec_b64 s[0:1], vcc
	s_xor_b64 s[0:1], exec, s[0:1]
	v_add_u32_e32 v64, 0xffffff78, v103
	v_mul_hi_u32 v65, v64, s24
	v_lshrrev_b32_e32 v65, 1, v65
	v_lshl_add_u32 v112, v65, 8, v159
	v_lshl_add_u32 v65, v65, 1, v65
	v_sub_u32_e32 v98, v64, v65
	s_or_saveexec_b64 s[0:1], s[0:1]
	v_mov_b32_e32 v113, 0x100
	s_xor_b64 exec, exec, s[0:1]
	v_mul_hi_i32 v64, v103, s16
	v_lshrrev_b32_e32 v65, 31, v64
	v_ashrrev_i32_e32 v64, 3, v64
	v_add_u32_e32 v64, v64, v65
	v_lshlrev_b32_e32 v112, 11, v64
	v_lshl_add_u32 v64, v64, 4, v64
	v_sub_u32_e32 v98, v103, v64
	v_mov_b32_e32 v113, 0x800
	s_or_b64 exec, exec, s[0:1]
	v_lshlrev_b32_sdwa v64, v176, v160 dst_sel:DWORD dst_unused:UNUSED_PAD src0_sel:DWORD src1_sel:BYTE_0
	v_and_b32_e32 v99, 56, v64
	v_lshl_or_b32 v96, s20, 7, v99
	v_ashrrev_i32_e32 v97, 31, v96
	v_lshlrev_b64 v[76:77], 2, v[96:97]
	v_lshl_add_u64 v[64:65], s[8:9], 0, v[76:77]
	v_lshl_add_u64 v[68:69], s[12:13], 0, v[76:77]
	s_waitcnt vmcnt(0)
	v_mov_b64_e32 v[80:81], v[200:201]
	v_mov_b64_e32 v[82:83], v[202:203]
	s_nop 0
	v_mov_b64_e32 v[64:65], v[204:205]
	v_mov_b64_e32 v[66:67], v[206:207]
	s_nop 0
	v_mov_b64_e32 v[84:85], v[208:209]
	v_mov_b64_e32 v[86:87], v[210:211]
	v_mov_b64_e32 v[72:73], v[212:213]
	v_mov_b64_e32 v[74:75], v[214:215]
	v_lshl_add_u64 v[68:69], s[14:15], 0, v[76:77]
	v_lshl_add_u64 v[76:77], s[10:11], 0, v[76:77]
	v_mov_b64_e32 v[88:89], v[216:217]
	v_mov_b64_e32 v[90:91], v[218:219]
	s_nop 0
	v_mov_b64_e32 v[68:69], v[220:221]
	v_mov_b64_e32 v[70:71], v[222:223]
	s_nop 0
	v_mov_b64_e32 v[92:93], v[224:225]
	v_mov_b64_e32 v[94:95], v[226:227]
	s_nop 0
	v_mov_b64_e32 v[76:77], v[228:229]
	v_mov_b64_e32 v[78:79], v[230:231]
	global_load_dwordx4 v[200:203], v[232:233], off offset:256
	global_load_dwordx4 v[204:207], v[232:233], off offset:272
	global_load_dwordx4 v[208:211], v[234:235], off offset:256
	global_load_dwordx4 v[212:215], v[234:235], off offset:272
	global_load_dwordx4 v[216:219], v[236:237], off offset:256
	global_load_dwordx4 v[220:223], v[236:237], off offset:272
	global_load_dwordx4 v[224:227], v[238:239], off offset:256
	global_load_dwordx4 v[228:231], v[238:239], off offset:272
	v_bfe_u32 v106, v160, 3, 5
	v_lshlrev_b32_e32 v108, 2, v99
	v_mad_u64_u32 v[98:99], s[0:1], v98, s26, -1
	v_mul_i32_i24_e32 v102, 0x12000, v161
	v_mul_u32_u24_e32 v100, 0x210, v106
	v_add_u32_e32 v99, v98, v106
	v_cmp_gt_u32_sdwa s[20:21], v160, v177 src0_sel:BYTE_0 src1_sel:DWORD
	v_add3_u32 v100, v102, v100, v108
	v_cmp_lt_i32_e64 s[0:1], v99, v113
	v_add_u32_e32 v104, 0xfffffdf0, v100
	s_and_b64 s[6:7], s[20:21], s[0:1]
	s_and_saveexec_b64 s[0:1], s[6:7]
	s_cbranch_execz .LBB0_2009
	s_mov_b32 s98, 0xbfb8aa3b
	ds_read_b128 v[114:117], v100
	ds_read_b128 v[164:167], v100 offset:16
	ds_read_b128 v[118:121], v104
	ds_read_b128 v[122:125], v104 offset:16
	ds_read_b128 v[160:163], v100 offset:528
	ds_read_b128 v[168:171], v100 offset:544
	ds_read_b128 v[172:175], v100 offset:256
	ds_read_b128 v[178:181], v100 offset:272
	s_waitcnt lgkmcnt(6)
	v_pk_mul_f32 v[114:115], v[84:85], v[114:115]
	v_pk_mul_f32 v[116:117], v[86:87], v[116:117]
	v_pk_mul_f32 v[164:165], v[72:73], v[164:165]
	v_pk_mul_f32 v[166:167], v[74:75], v[166:167]
	s_waitcnt lgkmcnt(4)
	v_pk_fma_f32 v[114:115], v[80:81], v[118:119], v[114:115]
	v_pk_fma_f32 v[116:117], v[82:83], v[120:121], v[116:117]
	v_pk_fma_f32 v[164:165], v[64:65], v[122:123], v[164:165]
	v_pk_fma_f32 v[166:167], v[66:67], v[124:125], v[166:167]
	s_waitcnt lgkmcnt(2)
	v_pk_fma_f32 v[114:115], v[88:89], v[160:161], v[114:115]
	v_pk_fma_f32 v[116:117], v[90:91], v[162:163], v[116:117]
	v_pk_fma_f32 v[164:165], v[68:69], v[168:169], v[164:165]
	v_pk_fma_f32 v[166:167], v[70:71], v[170:171], v[166:167]
	v_pk_add_f32 v[114:115], v[92:93], v[114:115]
	v_pk_add_f32 v[116:117], v[94:95], v[116:117]
	v_pk_add_f32 v[164:165], v[76:77], v[164:165]
	v_pk_add_f32 v[166:167], v[78:79], v[166:167]
	v_pk_mul_f32 v[118:119], v[114:115], s[98:99] op_sel_hi:[1,0]
	v_pk_mul_f32 v[120:121], v[116:117], s[98:99] op_sel_hi:[1,0]
	v_pk_mul_f32 v[122:123], v[164:165], s[98:99] op_sel_hi:[1,0]
	v_pk_mul_f32 v[124:125], v[166:167], s[98:99] op_sel_hi:[1,0]
	v_exp_f32_e32 v118, v118
	v_exp_f32_e32 v119, v119
	v_exp_f32_e32 v120, v120
	v_exp_f32_e32 v121, v121
	v_exp_f32_e32 v122, v122
	v_exp_f32_e32 v123, v123
	v_exp_f32_e32 v124, v124
	v_exp_f32_e32 v125, v125
	v_pk_add_f32 v[118:119], v[118:119], 1.0 op_sel_hi:[1,0]
	v_pk_add_f32 v[120:121], v[120:121], 1.0 op_sel_hi:[1,0]
	v_pk_add_f32 v[122:123], v[122:123], 1.0 op_sel_hi:[1,0]
	v_pk_add_f32 v[124:125], v[124:125], 1.0 op_sel_hi:[1,0]
	v_rcp_f32_e32 v118, v118
	v_rcp_f32_e32 v119, v119
	v_rcp_f32_e32 v120, v120
	v_rcp_f32_e32 v121, v121
	v_rcp_f32_e32 v122, v122
	v_rcp_f32_e32 v123, v123
	v_rcp_f32_e32 v124, v124
	v_rcp_f32_e32 v125, v125
	v_pk_mul_f32 v[114:115], v[114:115], v[118:119]
	v_pk_mul_f32 v[116:117], v[116:117], v[120:121]
	v_pk_mul_f32 v[164:165], v[164:165], v[122:123]
	v_pk_mul_f32 v[166:167], v[166:167], v[124:125]
	s_waitcnt lgkmcnt(0)
	v_pk_mul_f32 v[114:115], v[172:173], v[114:115]
	v_pk_mul_f32 v[116:117], v[174:175], v[116:117]
	v_pk_mul_f32 v[164:165], v[178:179], v[164:165]
	v_pk_mul_f32 v[166:167], v[180:181], v[166:167]
	v_cvt_pk_bf16_f32 v248, v114, v115
	v_cvt_pk_bf16_f32 v249, v116, v117
	v_cvt_pk_bf16_f32 v250, v164, v165
	v_cvt_pk_bf16_f32 v251, v166, v167
	v_add_u32_e32 v99, v99, v112
	v_mov_b64_e32 v[110:111], s[52:53]
	v_mad_i64_i32 v[110:111], s[6:7], v99, s30, v[110:111]
	v_lshl_add_u64 v[110:111], v[96:97], 1, v[110:111]
	global_store_dwordx4 v[110:111], v[248:251], off
.LBB0_2009:
	s_or_b64 exec, exec, s[0:1]
	v_or_b32_e32 v109, 32, v106
	v_mul_u32_u24_e32 v99, 0x210, v109
	v_add3_u32 v99, v102, v99, v108
	v_add_u32_e32 v101, v98, v109
	v_add_u32_e32 v105, 0xfffffdf0, v99
	v_cmp_lt_i32_e64 s[0:1], v101, v113
	s_and_saveexec_b64 s[6:7], s[0:1]
	s_cbranch_execz .LBB0_2011
	s_mov_b32 s98, 0xbfb8aa3b
	ds_read_b128 v[114:117], v99
	ds_read_b128 v[164:167], v99 offset:16
	ds_read_b128 v[118:121], v105
	ds_read_b128 v[122:125], v105 offset:16
	ds_read_b128 v[160:163], v99 offset:528
	ds_read_b128 v[168:171], v99 offset:544
	ds_read_b128 v[172:175], v99 offset:256
	ds_read_b128 v[178:181], v99 offset:272
	s_waitcnt lgkmcnt(6)
	v_pk_mul_f32 v[114:115], v[84:85], v[114:115]
	v_pk_mul_f32 v[116:117], v[86:87], v[116:117]
	v_pk_mul_f32 v[164:165], v[72:73], v[164:165]
	v_pk_mul_f32 v[166:167], v[74:75], v[166:167]
	s_waitcnt lgkmcnt(4)
	v_pk_fma_f32 v[114:115], v[80:81], v[118:119], v[114:115]
	v_pk_fma_f32 v[116:117], v[82:83], v[120:121], v[116:117]
	v_pk_fma_f32 v[164:165], v[64:65], v[122:123], v[164:165]
	v_pk_fma_f32 v[166:167], v[66:67], v[124:125], v[166:167]
	s_waitcnt lgkmcnt(2)
	v_pk_fma_f32 v[114:115], v[88:89], v[160:161], v[114:115]
	v_pk_fma_f32 v[116:117], v[90:91], v[162:163], v[116:117]
	v_pk_fma_f32 v[164:165], v[68:69], v[168:169], v[164:165]
	v_pk_fma_f32 v[166:167], v[70:71], v[170:171], v[166:167]
	v_pk_add_f32 v[114:115], v[92:93], v[114:115]
	v_pk_add_f32 v[116:117], v[94:95], v[116:117]
	v_pk_add_f32 v[164:165], v[76:77], v[164:165]
	v_pk_add_f32 v[166:167], v[78:79], v[166:167]
	v_pk_mul_f32 v[118:119], v[114:115], s[98:99] op_sel_hi:[1,0]
	v_pk_mul_f32 v[120:121], v[116:117], s[98:99] op_sel_hi:[1,0]
	v_pk_mul_f32 v[122:123], v[164:165], s[98:99] op_sel_hi:[1,0]
	v_pk_mul_f32 v[124:125], v[166:167], s[98:99] op_sel_hi:[1,0]
	v_exp_f32_e32 v118, v118
	v_exp_f32_e32 v119, v119
	v_exp_f32_e32 v120, v120
	v_exp_f32_e32 v121, v121
	v_exp_f32_e32 v122, v122
	v_exp_f32_e32 v123, v123
	v_exp_f32_e32 v124, v124
	v_exp_f32_e32 v125, v125
	v_pk_add_f32 v[118:119], v[118:119], 1.0 op_sel_hi:[1,0]
	v_pk_add_f32 v[120:121], v[120:121], 1.0 op_sel_hi:[1,0]
	v_pk_add_f32 v[122:123], v[122:123], 1.0 op_sel_hi:[1,0]
	v_pk_add_f32 v[124:125], v[124:125], 1.0 op_sel_hi:[1,0]
	v_rcp_f32_e32 v118, v118
	v_rcp_f32_e32 v119, v119
	v_rcp_f32_e32 v120, v120
	v_rcp_f32_e32 v121, v121
	v_rcp_f32_e32 v122, v122
	v_rcp_f32_e32 v123, v123
	v_rcp_f32_e32 v124, v124
	v_rcp_f32_e32 v125, v125
	v_pk_mul_f32 v[114:115], v[114:115], v[118:119]
	v_pk_mul_f32 v[116:117], v[116:117], v[120:121]
	v_pk_mul_f32 v[164:165], v[164:165], v[122:123]
	v_pk_mul_f32 v[166:167], v[166:167], v[124:125]
	s_waitcnt lgkmcnt(0)
	v_pk_mul_f32 v[114:115], v[172:173], v[114:115]
	v_pk_mul_f32 v[116:117], v[174:175], v[116:117]
	v_pk_mul_f32 v[164:165], v[178:179], v[164:165]
	v_pk_mul_f32 v[166:167], v[180:181], v[166:167]
	v_cvt_pk_bf16_f32 v248, v114, v115
	v_cvt_pk_bf16_f32 v249, v116, v117
	v_cvt_pk_bf16_f32 v250, v164, v165
	v_cvt_pk_bf16_f32 v251, v166, v167
	v_add_u32_e32 v101, v101, v112
	v_mov_b64_e32 v[110:111], s[52:53]
	v_mad_i64_i32 v[110:111], s[0:1], v101, s30, v[110:111]
	v_lshl_add_u64 v[110:111], v[96:97], 1, v[110:111]
	global_store_dwordx4 v[110:111], v[248:251], off
.LBB0_2011:
	s_or_b64 exec, exec, s[6:7]
	v_or_b32_e32 v110, 64, v106
	v_mul_u32_u24_e32 v101, 0x210, v110
	v_add3_u32 v101, v102, v101, v108
	v_add_u32_e32 v111, v98, v110
	v_add_u32_e32 v107, 0xfffffdf0, v101
	v_cmp_lt_i32_e64 s[0:1], v111, v113
	s_and_saveexec_b64 s[6:7], s[0:1]
	s_cbranch_execz .LBB0_2013
	s_mov_b32 s98, 0xbfb8aa3b
	ds_read_b128 v[114:117], v101
	ds_read_b128 v[164:167], v101 offset:16
	ds_read_b128 v[118:121], v107
	ds_read_b128 v[122:125], v107 offset:16
	ds_read_b128 v[160:163], v101 offset:528
	ds_read_b128 v[168:171], v101 offset:544
	ds_read_b128 v[172:175], v101 offset:256
	ds_read_b128 v[178:181], v101 offset:272
	s_waitcnt lgkmcnt(6)
	v_pk_mul_f32 v[114:115], v[84:85], v[114:115]
	v_pk_mul_f32 v[116:117], v[86:87], v[116:117]
	v_pk_mul_f32 v[164:165], v[72:73], v[164:165]
	v_pk_mul_f32 v[166:167], v[74:75], v[166:167]
	s_waitcnt lgkmcnt(4)
	v_pk_fma_f32 v[114:115], v[80:81], v[118:119], v[114:115]
	v_pk_fma_f32 v[116:117], v[82:83], v[120:121], v[116:117]
	v_pk_fma_f32 v[164:165], v[64:65], v[122:123], v[164:165]
	v_pk_fma_f32 v[166:167], v[66:67], v[124:125], v[166:167]
	s_waitcnt lgkmcnt(2)
	v_pk_fma_f32 v[114:115], v[88:89], v[160:161], v[114:115]
	v_pk_fma_f32 v[116:117], v[90:91], v[162:163], v[116:117]
	v_pk_fma_f32 v[164:165], v[68:69], v[168:169], v[164:165]
	v_pk_fma_f32 v[166:167], v[70:71], v[170:171], v[166:167]
	v_pk_add_f32 v[114:115], v[92:93], v[114:115]
	v_pk_add_f32 v[116:117], v[94:95], v[116:117]
	v_pk_add_f32 v[164:165], v[76:77], v[164:165]
	v_pk_add_f32 v[166:167], v[78:79], v[166:167]
	v_pk_mul_f32 v[118:119], v[114:115], s[98:99] op_sel_hi:[1,0]
	v_pk_mul_f32 v[120:121], v[116:117], s[98:99] op_sel_hi:[1,0]
	v_pk_mul_f32 v[122:123], v[164:165], s[98:99] op_sel_hi:[1,0]
	v_pk_mul_f32 v[124:125], v[166:167], s[98:99] op_sel_hi:[1,0]
	v_exp_f32_e32 v118, v118
	v_exp_f32_e32 v119, v119
	v_exp_f32_e32 v120, v120
	v_exp_f32_e32 v121, v121
	v_exp_f32_e32 v122, v122
	v_exp_f32_e32 v123, v123
	v_exp_f32_e32 v124, v124
	v_exp_f32_e32 v125, v125
	v_pk_add_f32 v[118:119], v[118:119], 1.0 op_sel_hi:[1,0]
	v_pk_add_f32 v[120:121], v[120:121], 1.0 op_sel_hi:[1,0]
	v_pk_add_f32 v[122:123], v[122:123], 1.0 op_sel_hi:[1,0]
	v_pk_add_f32 v[124:125], v[124:125], 1.0 op_sel_hi:[1,0]
	v_rcp_f32_e32 v118, v118
	v_rcp_f32_e32 v119, v119
	v_rcp_f32_e32 v120, v120
	v_rcp_f32_e32 v121, v121
	v_rcp_f32_e32 v122, v122
	v_rcp_f32_e32 v123, v123
	v_rcp_f32_e32 v124, v124
	v_rcp_f32_e32 v125, v125
	v_pk_mul_f32 v[114:115], v[114:115], v[118:119]
	v_pk_mul_f32 v[116:117], v[116:117], v[120:121]
	v_pk_mul_f32 v[164:165], v[164:165], v[122:123]
	v_pk_mul_f32 v[166:167], v[166:167], v[124:125]
	s_waitcnt lgkmcnt(0)
	v_pk_mul_f32 v[114:115], v[172:173], v[114:115]
	v_pk_mul_f32 v[116:117], v[174:175], v[116:117]
	v_pk_mul_f32 v[164:165], v[178:179], v[164:165]
	v_pk_mul_f32 v[166:167], v[180:181], v[166:167]
	v_cvt_pk_bf16_f32 v248, v114, v115
	v_cvt_pk_bf16_f32 v249, v116, v117
	v_cvt_pk_bf16_f32 v250, v164, v165
	v_cvt_pk_bf16_f32 v251, v166, v167
	v_add_u32_e32 v111, v111, v112
	v_mov_b64_e32 v[118:119], s[52:53]
	v_mad_i64_i32 v[118:119], s[0:1], v111, s30, v[118:119]
	v_lshl_add_u64 v[118:119], v[96:97], 1, v[118:119]
	global_store_dwordx4 v[118:119], v[248:251], off
.LBB0_2013:
	s_or_b64 exec, exec, s[6:7]
	v_or_b32_e32 v111, 0x60, v106
	v_mul_u32_u24_e32 v114, 0x210, v111
	v_add_u32_e32 v98, v98, v111
	v_cmp_ne_u32_e64 s[0:1], 31, v106
	v_add3_u32 v102, v102, v114, v108
	v_cmp_lt_i32_e64 s[6:7], v98, v113
	v_add_u32_e32 v108, 0xfffffdf0, v102
	s_and_b64 s[34:35], s[0:1], s[6:7]
	s_and_saveexec_b64 s[6:7], s[34:35]
	s_cbranch_execz .LBB0_2015
	s_mov_b32 s98, 0xbfb8aa3b
	ds_read_b128 v[114:117], v102
	ds_read_b128 v[164:167], v102 offset:16
	ds_read_b128 v[118:121], v108
	ds_read_b128 v[122:125], v108 offset:16
	ds_read_b128 v[160:163], v102 offset:528
	ds_read_b128 v[168:171], v102 offset:544
	ds_read_b128 v[172:175], v102 offset:256
	ds_read_b128 v[178:181], v102 offset:272
	s_waitcnt lgkmcnt(6)
	v_pk_mul_f32 v[114:115], v[84:85], v[114:115]
	v_pk_mul_f32 v[116:117], v[86:87], v[116:117]
	v_pk_mul_f32 v[164:165], v[72:73], v[164:165]
	v_pk_mul_f32 v[166:167], v[74:75], v[166:167]
	s_waitcnt lgkmcnt(4)
	v_pk_fma_f32 v[114:115], v[80:81], v[118:119], v[114:115]
	v_pk_fma_f32 v[116:117], v[82:83], v[120:121], v[116:117]
	v_pk_fma_f32 v[164:165], v[64:65], v[122:123], v[164:165]
	v_pk_fma_f32 v[166:167], v[66:67], v[124:125], v[166:167]
	s_waitcnt lgkmcnt(2)
	v_pk_fma_f32 v[114:115], v[88:89], v[160:161], v[114:115]
	v_pk_fma_f32 v[116:117], v[90:91], v[162:163], v[116:117]
	v_pk_fma_f32 v[164:165], v[68:69], v[168:169], v[164:165]
	v_pk_fma_f32 v[166:167], v[70:71], v[170:171], v[166:167]
	v_pk_add_f32 v[114:115], v[92:93], v[114:115]
	v_pk_add_f32 v[116:117], v[94:95], v[116:117]
	v_pk_add_f32 v[164:165], v[76:77], v[164:165]
	v_pk_add_f32 v[166:167], v[78:79], v[166:167]
	v_pk_mul_f32 v[118:119], v[114:115], s[98:99] op_sel_hi:[1,0]
	v_pk_mul_f32 v[120:121], v[116:117], s[98:99] op_sel_hi:[1,0]
	v_pk_mul_f32 v[122:123], v[164:165], s[98:99] op_sel_hi:[1,0]
	v_pk_mul_f32 v[124:125], v[166:167], s[98:99] op_sel_hi:[1,0]
	v_exp_f32_e32 v118, v118
	v_exp_f32_e32 v119, v119
	v_exp_f32_e32 v120, v120
	v_exp_f32_e32 v121, v121
	v_exp_f32_e32 v122, v122
	v_exp_f32_e32 v123, v123
	v_exp_f32_e32 v124, v124
	v_exp_f32_e32 v125, v125
	v_pk_add_f32 v[118:119], v[118:119], 1.0 op_sel_hi:[1,0]
	v_pk_add_f32 v[120:121], v[120:121], 1.0 op_sel_hi:[1,0]
	v_pk_add_f32 v[122:123], v[122:123], 1.0 op_sel_hi:[1,0]
	v_pk_add_f32 v[124:125], v[124:125], 1.0 op_sel_hi:[1,0]
	v_rcp_f32_e32 v118, v118
	v_rcp_f32_e32 v119, v119
	v_rcp_f32_e32 v120, v120
	v_rcp_f32_e32 v121, v121
	v_rcp_f32_e32 v122, v122
	v_rcp_f32_e32 v123, v123
	v_rcp_f32_e32 v124, v124
	v_rcp_f32_e32 v125, v125
	v_pk_mul_f32 v[114:115], v[114:115], v[118:119]
	v_pk_mul_f32 v[116:117], v[116:117], v[120:121]
	v_pk_mul_f32 v[164:165], v[164:165], v[122:123]
	v_pk_mul_f32 v[166:167], v[166:167], v[124:125]
	s_waitcnt lgkmcnt(0)
	v_pk_mul_f32 v[114:115], v[172:173], v[114:115]
	v_pk_mul_f32 v[116:117], v[174:175], v[116:117]
	v_pk_mul_f32 v[164:165], v[178:179], v[164:165]
	v_pk_mul_f32 v[166:167], v[180:181], v[166:167]
	v_cvt_pk_bf16_f32 v248, v114, v115
	v_cvt_pk_bf16_f32 v249, v116, v117
	v_cvt_pk_bf16_f32 v250, v164, v165
	v_cvt_pk_bf16_f32 v251, v166, v167
	v_add_u32_e32 v70, v98, v112
	v_mov_b64_e32 v[68:69], s[52:53]
	v_mad_i64_i32 v[68:69], s[34:35], v70, s30, v[68:69]
	v_lshl_add_u64 v[68:69], v[96:97], 1, v[68:69]
	global_store_dwordx4 v[68:69], v[248:251], off
.LBB0_2015:
	s_or_b64 exec, exec, s[6:7]
	s_barrier
	ds_write_b128 v132, v[60:63]
	ds_write_b128 v132, v[56:59] offset:64
	ds_write_b128 v132, v[52:55] offset:8448
	ds_write_b128 v132, v[48:51] offset:8512
	ds_write_b128 v132, v[44:47] offset:16896
	ds_write_b128 v132, v[40:43] offset:16960
	ds_write_b128 v132, v[36:39] offset:25344
	ds_write_b128 v132, v[32:35] offset:25408
	ds_write_b128 v132, v[28:31] offset:33792
	ds_write_b128 v132, v[24:27] offset:33856
	ds_write_b128 v132, v[20:23] offset:42240
	ds_write_b128 v132, v[16:19] offset:42304
	ds_write_b128 v132, v[12:15] offset:50688
	ds_write_b128 v132, v[8:11] offset:50752
	ds_write_b128 v132, v[4:7] offset:59136
	ds_write_b128 v132, v[0:3] offset:59200
	s_waitcnt lgkmcnt(0)
	s_barrier
	s_and_saveexec_b64 s[6:7], vcc
	s_xor_b64 s[6:7], exec, s[6:7]
	v_add_u32_e32 v0, 0xffffff78, v103
	v_mul_hi_u32 v1, v0, s24
	v_lshrrev_b32_e32 v1, 1, v1
	v_lshl_add_u32 v34, v1, 8, v159
	v_lshl_add_u32 v1, v1, 1, v1
	v_sub_u32_e32 v32, v0, v1
	s_or_saveexec_b64 s[6:7], s[6:7]
	v_mov_b32_e32 v35, 0x100
	s_xor_b64 exec, exec, s[6:7]
	v_mul_hi_i32 v0, v103, s16
	v_lshrrev_b32_e32 v1, 31, v0
	v_ashrrev_i32_e32 v0, 3, v0
	v_add_u32_e32 v0, v0, v1
	v_lshlrev_b32_e32 v34, 11, v0
	v_lshl_add_u32 v0, v0, 4, v0
	v_sub_u32_e32 v32, v103, v0
	v_mov_b32_e32 v35, 0x800
	s_or_b64 exec, exec, s[6:7]
	v_or_b32_e32 v0, 64, v96
	v_ashrrev_i32_e32 v1, 31, v0
	v_lshlrev_b64 v[12:13], 2, v[0:1]
	v_lshl_add_u64 v[4:5], s[8:9], 0, v[12:13]
	v_lshl_add_u64 v[8:9], s[12:13], 0, v[12:13]
	v_lshl_add_u64 v[14:15], s[14:15], 0, v[12:13]
	v_lshl_add_u64 v[36:37], s[10:11], 0, v[12:13]
	s_waitcnt vmcnt(0)
	v_mov_b64_e32 v[16:17], v[200:201]
	v_mov_b64_e32 v[18:19], v[202:203]
	v_mov_b64_e32 v[0:1], v[204:205]
	v_mov_b64_e32 v[2:3], v[206:207]
	v_mov_b64_e32 v[20:21], v[208:209]
	v_mov_b64_e32 v[22:23], v[210:211]
	s_nop 0
	v_mov_b64_e32 v[4:5], v[212:213]
	v_mov_b64_e32 v[6:7], v[214:215]
	v_mov_b64_e32 v[24:25], v[216:217]
	v_mov_b64_e32 v[26:27], v[218:219]
	s_nop 0
	v_mov_b64_e32 v[8:9], v[220:221]
	v_mov_b64_e32 v[10:11], v[222:223]
	v_mov_b64_e32 v[28:29], v[224:225]
	v_mov_b64_e32 v[30:31], v[226:227]
	s_nop 0
	v_mov_b64_e32 v[12:13], v[228:229]
	v_mov_b64_e32 v[14:15], v[230:231]
	v_mad_u64_u32 v[32:33], s[6:7], v32, s26, -1
	v_add_u32_e32 v33, v32, v106
	v_cmp_lt_i32_e32 vcc, v33, v35
	s_and_b64 s[20:21], s[20:21], vcc
	s_and_saveexec_b64 s[6:7], s[20:21]
	s_cbranch_execz .LBB0_2021
	s_mov_b32 s98, 0xbfb8aa3b
	ds_read_b128 v[36:39], v100
	ds_read_b128 v[52:55], v100 offset:16
	ds_read_b128 v[40:43], v104
	ds_read_b128 v[44:47], v104 offset:16
	ds_read_b128 v[48:51], v100 offset:528
	ds_read_b128 v[56:59], v100 offset:544
	ds_read_b128 v[60:63], v100 offset:256
	ds_read_b128 v[64:67], v100 offset:272
	s_waitcnt lgkmcnt(6)
	v_pk_mul_f32 v[36:37], v[20:21], v[36:37]
	v_pk_mul_f32 v[38:39], v[22:23], v[38:39]
	v_pk_mul_f32 v[52:53], v[4:5], v[52:53]
	v_pk_mul_f32 v[54:55], v[6:7], v[54:55]
	s_waitcnt lgkmcnt(4)
	v_pk_fma_f32 v[36:37], v[16:17], v[40:41], v[36:37]
	v_pk_fma_f32 v[38:39], v[18:19], v[42:43], v[38:39]
	v_pk_fma_f32 v[52:53], v[0:1], v[44:45], v[52:53]
	v_pk_fma_f32 v[54:55], v[2:3], v[46:47], v[54:55]
	s_waitcnt lgkmcnt(2)
	v_pk_fma_f32 v[36:37], v[24:25], v[48:49], v[36:37]
	v_pk_fma_f32 v[38:39], v[26:27], v[50:51], v[38:39]
	v_pk_fma_f32 v[52:53], v[8:9], v[56:57], v[52:53]
	v_pk_fma_f32 v[54:55], v[10:11], v[58:59], v[54:55]
	v_pk_add_f32 v[36:37], v[28:29], v[36:37]
	v_pk_add_f32 v[38:39], v[30:31], v[38:39]
	v_pk_add_f32 v[52:53], v[12:13], v[52:53]
	v_pk_add_f32 v[54:55], v[14:15], v[54:55]
	v_pk_mul_f32 v[40:41], v[36:37], s[98:99] op_sel_hi:[1,0]
	v_pk_mul_f32 v[42:43], v[38:39], s[98:99] op_sel_hi:[1,0]
	v_pk_mul_f32 v[44:45], v[52:53], s[98:99] op_sel_hi:[1,0]
	v_pk_mul_f32 v[46:47], v[54:55], s[98:99] op_sel_hi:[1,0]
	v_exp_f32_e32 v40, v40
	v_exp_f32_e32 v41, v41
	v_exp_f32_e32 v42, v42
	v_exp_f32_e32 v43, v43
	v_exp_f32_e32 v44, v44
	v_exp_f32_e32 v45, v45
	v_exp_f32_e32 v46, v46
	v_exp_f32_e32 v47, v47
	v_pk_add_f32 v[40:41], v[40:41], 1.0 op_sel_hi:[1,0]
	v_pk_add_f32 v[42:43], v[42:43], 1.0 op_sel_hi:[1,0]
	v_pk_add_f32 v[44:45], v[44:45], 1.0 op_sel_hi:[1,0]
	v_pk_add_f32 v[46:47], v[46:47], 1.0 op_sel_hi:[1,0]
	v_rcp_f32_e32 v40, v40
	v_rcp_f32_e32 v41, v41
	v_rcp_f32_e32 v42, v42
	v_rcp_f32_e32 v43, v43
	v_rcp_f32_e32 v44, v44
	v_rcp_f32_e32 v45, v45
	v_rcp_f32_e32 v46, v46
	v_rcp_f32_e32 v47, v47
	v_pk_mul_f32 v[36:37], v[36:37], v[40:41]
	v_pk_mul_f32 v[38:39], v[38:39], v[42:43]
	v_pk_mul_f32 v[52:53], v[52:53], v[44:45]
	v_pk_mul_f32 v[54:55], v[54:55], v[46:47]
	s_waitcnt lgkmcnt(0)
	v_pk_mul_f32 v[36:37], v[60:61], v[36:37]
	v_pk_mul_f32 v[38:39], v[62:63], v[38:39]
	v_pk_mul_f32 v[52:53], v[64:65], v[52:53]
	v_pk_mul_f32 v[54:55], v[66:67], v[54:55]
	v_cvt_pk_bf16_f32 v248, v36, v37
	v_cvt_pk_bf16_f32 v249, v38, v39
	v_cvt_pk_bf16_f32 v250, v52, v53
	v_cvt_pk_bf16_f32 v251, v54, v55
	v_add_u32_e32 v33, v33, v34
	v_mov_b64_e32 v[40:41], s[52:53]
	v_mad_i64_i32 v[40:41], s[20:21], v33, s30, v[40:41]
	v_lshl_add_u64 v[40:41], v[96:97], 1, v[40:41]
	global_store_dwordx4 v[40:41], v[248:251], off offset:128
.LBB0_2021:
	s_or_b64 exec, exec, s[6:7]
	v_add_u32_e32 v33, v32, v109
	v_cmp_lt_i32_e32 vcc, v33, v35
	s_and_saveexec_b64 s[6:7], vcc
	s_cbranch_execz .LBB0_2023
	s_mov_b32 s98, 0xbfb8aa3b
	ds_read_b128 v[36:39], v99
	ds_read_b128 v[52:55], v99 offset:16
	ds_read_b128 v[40:43], v105
	ds_read_b128 v[44:47], v105 offset:16
	ds_read_b128 v[48:51], v99 offset:528
	ds_read_b128 v[56:59], v99 offset:544
	ds_read_b128 v[60:63], v99 offset:256
	ds_read_b128 v[64:67], v99 offset:272
	s_waitcnt lgkmcnt(6)
	v_pk_mul_f32 v[36:37], v[20:21], v[36:37]
	v_pk_mul_f32 v[38:39], v[22:23], v[38:39]
	v_pk_mul_f32 v[52:53], v[4:5], v[52:53]
	v_pk_mul_f32 v[54:55], v[6:7], v[54:55]
	s_waitcnt lgkmcnt(4)
	v_pk_fma_f32 v[36:37], v[16:17], v[40:41], v[36:37]
	v_pk_fma_f32 v[38:39], v[18:19], v[42:43], v[38:39]
	v_pk_fma_f32 v[52:53], v[0:1], v[44:45], v[52:53]
	v_pk_fma_f32 v[54:55], v[2:3], v[46:47], v[54:55]
	s_waitcnt lgkmcnt(2)
	v_pk_fma_f32 v[36:37], v[24:25], v[48:49], v[36:37]
	v_pk_fma_f32 v[38:39], v[26:27], v[50:51], v[38:39]
	v_pk_fma_f32 v[52:53], v[8:9], v[56:57], v[52:53]
	v_pk_fma_f32 v[54:55], v[10:11], v[58:59], v[54:55]
	v_pk_add_f32 v[36:37], v[28:29], v[36:37]
	v_pk_add_f32 v[38:39], v[30:31], v[38:39]
	v_pk_add_f32 v[52:53], v[12:13], v[52:53]
	v_pk_add_f32 v[54:55], v[14:15], v[54:55]
	v_pk_mul_f32 v[40:41], v[36:37], s[98:99] op_sel_hi:[1,0]
	v_pk_mul_f32 v[42:43], v[38:39], s[98:99] op_sel_hi:[1,0]
	v_pk_mul_f32 v[44:45], v[52:53], s[98:99] op_sel_hi:[1,0]
	v_pk_mul_f32 v[46:47], v[54:55], s[98:99] op_sel_hi:[1,0]
	v_exp_f32_e32 v40, v40
	v_exp_f32_e32 v41, v41
	v_exp_f32_e32 v42, v42
	v_exp_f32_e32 v43, v43
	v_exp_f32_e32 v44, v44
	v_exp_f32_e32 v45, v45
	v_exp_f32_e32 v46, v46
	v_exp_f32_e32 v47, v47
	v_pk_add_f32 v[40:41], v[40:41], 1.0 op_sel_hi:[1,0]
	v_pk_add_f32 v[42:43], v[42:43], 1.0 op_sel_hi:[1,0]
	v_pk_add_f32 v[44:45], v[44:45], 1.0 op_sel_hi:[1,0]
	v_pk_add_f32 v[46:47], v[46:47], 1.0 op_sel_hi:[1,0]
	v_rcp_f32_e32 v40, v40
	v_rcp_f32_e32 v41, v41
	v_rcp_f32_e32 v42, v42
	v_rcp_f32_e32 v43, v43
	v_rcp_f32_e32 v44, v44
	v_rcp_f32_e32 v45, v45
	v_rcp_f32_e32 v46, v46
	v_rcp_f32_e32 v47, v47
	v_pk_mul_f32 v[36:37], v[36:37], v[40:41]
	v_pk_mul_f32 v[38:39], v[38:39], v[42:43]
	v_pk_mul_f32 v[52:53], v[52:53], v[44:45]
	v_pk_mul_f32 v[54:55], v[54:55], v[46:47]
	s_waitcnt lgkmcnt(0)
	v_pk_mul_f32 v[36:37], v[60:61], v[36:37]
	v_pk_mul_f32 v[38:39], v[62:63], v[38:39]
	v_pk_mul_f32 v[52:53], v[64:65], v[52:53]
	v_pk_mul_f32 v[54:55], v[66:67], v[54:55]
	v_cvt_pk_bf16_f32 v248, v36, v37
	v_cvt_pk_bf16_f32 v249, v38, v39
	v_cvt_pk_bf16_f32 v250, v52, v53
	v_cvt_pk_bf16_f32 v251, v54, v55
	v_add_u32_e32 v33, v33, v34
	v_mov_b64_e32 v[40:41], s[52:53]
	v_mad_i64_i32 v[40:41], s[20:21], v33, s30, v[40:41]
	v_lshl_add_u64 v[40:41], v[96:97], 1, v[40:41]
	global_store_dwordx4 v[40:41], v[248:251], off offset:128
.LBB0_2023:
	s_or_b64 exec, exec, s[6:7]
	v_add_u32_e32 v33, v32, v110
	v_cmp_lt_i32_e32 vcc, v33, v35
	s_and_saveexec_b64 s[6:7], vcc
	s_cbranch_execz .LBB0_2025
	s_mov_b32 s98, 0xbfb8aa3b
	ds_read_b128 v[36:39], v101
	ds_read_b128 v[52:55], v101 offset:16
	ds_read_b128 v[40:43], v107
	ds_read_b128 v[44:47], v107 offset:16
	ds_read_b128 v[48:51], v101 offset:528
	ds_read_b128 v[56:59], v101 offset:544
	ds_read_b128 v[60:63], v101 offset:256
	ds_read_b128 v[64:67], v101 offset:272
	s_waitcnt lgkmcnt(6)
	v_pk_mul_f32 v[36:37], v[20:21], v[36:37]
	v_pk_mul_f32 v[38:39], v[22:23], v[38:39]
	v_pk_mul_f32 v[52:53], v[4:5], v[52:53]
	v_pk_mul_f32 v[54:55], v[6:7], v[54:55]
	s_waitcnt lgkmcnt(4)
	v_pk_fma_f32 v[36:37], v[16:17], v[40:41], v[36:37]
	v_pk_fma_f32 v[38:39], v[18:19], v[42:43], v[38:39]
	v_pk_fma_f32 v[52:53], v[0:1], v[44:45], v[52:53]
	v_pk_fma_f32 v[54:55], v[2:3], v[46:47], v[54:55]
	s_waitcnt lgkmcnt(2)
	v_pk_fma_f32 v[36:37], v[24:25], v[48:49], v[36:37]
	v_pk_fma_f32 v[38:39], v[26:27], v[50:51], v[38:39]
	v_pk_fma_f32 v[52:53], v[8:9], v[56:57], v[52:53]
	v_pk_fma_f32 v[54:55], v[10:11], v[58:59], v[54:55]
	v_pk_add_f32 v[36:37], v[28:29], v[36:37]
	v_pk_add_f32 v[38:39], v[30:31], v[38:39]
	v_pk_add_f32 v[52:53], v[12:13], v[52:53]
	v_pk_add_f32 v[54:55], v[14:15], v[54:55]
	v_pk_mul_f32 v[40:41], v[36:37], s[98:99] op_sel_hi:[1,0]
	v_pk_mul_f32 v[42:43], v[38:39], s[98:99] op_sel_hi:[1,0]
	v_pk_mul_f32 v[44:45], v[52:53], s[98:99] op_sel_hi:[1,0]
	v_pk_mul_f32 v[46:47], v[54:55], s[98:99] op_sel_hi:[1,0]
	v_exp_f32_e32 v40, v40
	v_exp_f32_e32 v41, v41
	v_exp_f32_e32 v42, v42
	v_exp_f32_e32 v43, v43
	v_exp_f32_e32 v44, v44
	v_exp_f32_e32 v45, v45
	v_exp_f32_e32 v46, v46
	v_exp_f32_e32 v47, v47
	v_pk_add_f32 v[40:41], v[40:41], 1.0 op_sel_hi:[1,0]
	v_pk_add_f32 v[42:43], v[42:43], 1.0 op_sel_hi:[1,0]
	v_pk_add_f32 v[44:45], v[44:45], 1.0 op_sel_hi:[1,0]
	v_pk_add_f32 v[46:47], v[46:47], 1.0 op_sel_hi:[1,0]
	v_rcp_f32_e32 v40, v40
	v_rcp_f32_e32 v41, v41
	v_rcp_f32_e32 v42, v42
	v_rcp_f32_e32 v43, v43
	v_rcp_f32_e32 v44, v44
	v_rcp_f32_e32 v45, v45
	v_rcp_f32_e32 v46, v46
	v_rcp_f32_e32 v47, v47
	v_pk_mul_f32 v[36:37], v[36:37], v[40:41]
	v_pk_mul_f32 v[38:39], v[38:39], v[42:43]
	v_pk_mul_f32 v[52:53], v[52:53], v[44:45]
	v_pk_mul_f32 v[54:55], v[54:55], v[46:47]
	s_waitcnt lgkmcnt(0)
	v_pk_mul_f32 v[36:37], v[60:61], v[36:37]
	v_pk_mul_f32 v[38:39], v[62:63], v[38:39]
	v_pk_mul_f32 v[52:53], v[64:65], v[52:53]
	v_pk_mul_f32 v[54:55], v[66:67], v[54:55]
	v_cvt_pk_bf16_f32 v248, v36, v37
	v_cvt_pk_bf16_f32 v249, v38, v39
	v_cvt_pk_bf16_f32 v250, v52, v53
	v_cvt_pk_bf16_f32 v251, v54, v55
	v_add_u32_e32 v33, v33, v34
	v_mov_b64_e32 v[40:41], s[52:53]
	v_mad_i64_i32 v[40:41], s[20:21], v33, s30, v[40:41]
	v_lshl_add_u64 v[40:41], v[96:97], 1, v[40:41]
	global_store_dwordx4 v[40:41], v[248:251], off offset:128
.LBB0_2025:
	s_or_b64 exec, exec, s[6:7]
	v_add_u32_e32 v32, v32, v111
	v_cmp_lt_i32_e32 vcc, v32, v35
	s_and_b64 s[6:7], s[0:1], vcc
	s_and_saveexec_b64 s[0:1], s[6:7]
	s_cbranch_execz .LBB0_1987
	s_mov_b32 s98, 0xbfb8aa3b
	ds_read_b128 v[36:39], v102
	ds_read_b128 v[52:55], v102 offset:16
	ds_read_b128 v[40:43], v108
	ds_read_b128 v[44:47], v108 offset:16
	ds_read_b128 v[48:51], v102 offset:528
	ds_read_b128 v[56:59], v102 offset:544
	ds_read_b128 v[60:63], v102 offset:256
	ds_read_b128 v[64:67], v102 offset:272
	s_waitcnt lgkmcnt(6)
	v_pk_mul_f32 v[36:37], v[20:21], v[36:37]
	v_pk_mul_f32 v[38:39], v[22:23], v[38:39]
	v_pk_mul_f32 v[52:53], v[4:5], v[52:53]
	v_pk_mul_f32 v[54:55], v[6:7], v[54:55]
	s_waitcnt lgkmcnt(4)
	v_pk_fma_f32 v[36:37], v[16:17], v[40:41], v[36:37]
	v_pk_fma_f32 v[38:39], v[18:19], v[42:43], v[38:39]
	v_pk_fma_f32 v[52:53], v[0:1], v[44:45], v[52:53]
	v_pk_fma_f32 v[54:55], v[2:3], v[46:47], v[54:55]
	s_waitcnt lgkmcnt(2)
	v_pk_fma_f32 v[36:37], v[24:25], v[48:49], v[36:37]
	v_pk_fma_f32 v[38:39], v[26:27], v[50:51], v[38:39]
	v_pk_fma_f32 v[52:53], v[8:9], v[56:57], v[52:53]
	v_pk_fma_f32 v[54:55], v[10:11], v[58:59], v[54:55]
	v_pk_add_f32 v[36:37], v[28:29], v[36:37]
	v_pk_add_f32 v[38:39], v[30:31], v[38:39]
	v_pk_add_f32 v[52:53], v[12:13], v[52:53]
	v_pk_add_f32 v[54:55], v[14:15], v[54:55]
	v_pk_mul_f32 v[40:41], v[36:37], s[98:99] op_sel_hi:[1,0]
	v_pk_mul_f32 v[42:43], v[38:39], s[98:99] op_sel_hi:[1,0]
	v_pk_mul_f32 v[44:45], v[52:53], s[98:99] op_sel_hi:[1,0]
	v_pk_mul_f32 v[46:47], v[54:55], s[98:99] op_sel_hi:[1,0]
	v_exp_f32_e32 v40, v40
	v_exp_f32_e32 v41, v41
	v_exp_f32_e32 v42, v42
	v_exp_f32_e32 v43, v43
	v_exp_f32_e32 v44, v44
	v_exp_f32_e32 v45, v45
	v_exp_f32_e32 v46, v46
	v_exp_f32_e32 v47, v47
	v_pk_add_f32 v[40:41], v[40:41], 1.0 op_sel_hi:[1,0]
	v_pk_add_f32 v[42:43], v[42:43], 1.0 op_sel_hi:[1,0]
	v_pk_add_f32 v[44:45], v[44:45], 1.0 op_sel_hi:[1,0]
	v_pk_add_f32 v[46:47], v[46:47], 1.0 op_sel_hi:[1,0]
	v_rcp_f32_e32 v40, v40
	v_rcp_f32_e32 v41, v41
	v_rcp_f32_e32 v42, v42
	v_rcp_f32_e32 v43, v43
	v_rcp_f32_e32 v44, v44
	v_rcp_f32_e32 v45, v45
	v_rcp_f32_e32 v46, v46
	v_rcp_f32_e32 v47, v47
	v_pk_mul_f32 v[36:37], v[36:37], v[40:41]
	v_pk_mul_f32 v[38:39], v[38:39], v[42:43]
	v_pk_mul_f32 v[52:53], v[52:53], v[44:45]
	v_pk_mul_f32 v[54:55], v[54:55], v[46:47]
	s_waitcnt lgkmcnt(0)
	v_pk_mul_f32 v[36:37], v[60:61], v[36:37]
	v_pk_mul_f32 v[38:39], v[62:63], v[38:39]
	v_pk_mul_f32 v[52:53], v[64:65], v[52:53]
	v_pk_mul_f32 v[54:55], v[66:67], v[54:55]
	v_cvt_pk_bf16_f32 v248, v36, v37
	v_cvt_pk_bf16_f32 v249, v38, v39
	v_cvt_pk_bf16_f32 v250, v52, v53
	v_cvt_pk_bf16_f32 v251, v54, v55
	v_add_u32_e32 v6, v32, v34
	v_mov_b64_e32 v[4:5], s[52:53]
	v_mad_i64_i32 v[4:5], s[6:7], v6, s30, v[4:5]
	v_lshl_add_u64 v[4:5], v[96:97], 1, v[4:5]
	global_store_dwordx4 v[4:5], v[248:251], off offset:128
	s_branch .LBB0_1987
